# row-pair scan body with a single counted LDS wait per step
# baseline (speedup 1.0000x reference)
.Lsc_noinit:
	s_waitcnt lgkmcnt(0)
	v_pk_mul_f32 v[22:23], v[6:7], v[52:53] op_sel:[0,0] op_sel_hi:[1,0]
	v_pk_mul_f32 v[30:31], v[68:69], v[92:93] op_sel:[0,0] op_sel_hi:[0,1]
	ds_read_b128 v[94:97], v47 offset:256
	v_pk_fma_f32 v[22:23], v[8:9], v[52:53], v[22:23] op_sel:[0,1,0] op_sel_hi:[1,1,1]
	v_pk_mul_f32 v[32:33], v[68:69], v[92:93] op_sel:[1,0] op_sel_hi:[1,1]
	ds_read_b128 v[98:101], v47 offset:272
	v_pk_fma_f32 v[22:23], v[10:11], v[54:55], v[22:23] op_sel:[0,0,0] op_sel_hi:[1,0,1]
	v_pk_mul_f32 v[34:35], v[70:71], v[92:93] op_sel:[0,0] op_sel_hi:[0,1]
	ds_read_b128 v[110:113], v47 offset:8448
	v_pk_fma_f32 v[22:23], v[12:13], v[54:55], v[22:23] op_sel:[0,1,0] op_sel_hi:[1,1,1]
	v_pk_mul_f32 v[36:37], v[70:71], v[92:93] op_sel:[1,0] op_sel_hi:[1,1]
	ds_read_b128 v[114:117], v47 offset:8464
	v_pk_fma_f32 v[22:23], v[14:15], v[56:57], v[22:23] op_sel:[0,0,0] op_sel_hi:[1,0,1]
	v_pk_mul_f32 v[38:39], v[72:73], v[92:93] op_sel:[0,0] op_sel_hi:[0,1]
	ds_read_b64 v[134:135], v48 offset:256
	v_pk_fma_f32 v[22:23], v[16:17], v[56:57], v[22:23] op_sel:[0,1,0] op_sel_hi:[1,1,1]
	v_pk_mul_f32 v[40:41], v[72:73], v[92:93] op_sel:[1,0] op_sel_hi:[1,1]
	ds_read_b128 v[126:129], v47 offset:16640
	v_pk_fma_f32 v[22:23], v[18:19], v[58:59], v[22:23] op_sel:[0,0,0] op_sel_hi:[1,0,1]
	v_pk_mul_f32 v[42:43], v[74:75], v[92:93] op_sel:[0,0] op_sel_hi:[0,1]
	ds_read_b128 v[130:133], v47 offset:16656
	v_pk_fma_f32 v[22:23], v[20:21], v[58:59], v[22:23] op_sel:[0,1,0] op_sel_hi:[1,1,1]
	v_pk_mul_f32 v[44:45], v[74:75], v[92:93] op_sel:[1,0] op_sel_hi:[1,1]
	ds_read_b128 v[102:105], v47 offset:4352
	v_pk_fma_f32 v[30:31], v[84:85], v[6:7], v[30:31] op_sel:[0,0,0] op_sel_hi:[0,1,1]
	v_pk_fma_f32 v[32:33], v[84:85], v[8:9], v[32:33] op_sel:[1,0,0] op_sel_hi:[1,1,1]
	ds_read_b128 v[106:109], v47 offset:4368
	v_pk_fma_f32 v[34:35], v[86:87], v[10:11], v[34:35] op_sel:[0,0,0] op_sel_hi:[0,1,1]
	v_pk_fma_f32 v[36:37], v[86:87], v[12:13], v[36:37] op_sel:[1,0,0] op_sel_hi:[1,1,1]
	ds_read_b128 v[118:121], v47 offset:12544
	v_add_f32_dpp v22, v22, v22 quad_perm:[1,0,3,2] row_mask:0xf bank_mask:0xf
	v_add_f32_dpp v23, v23, v23 quad_perm:[1,0,3,2] row_mask:0xf bank_mask:0xf
	ds_read_b128 v[122:125], v47 offset:12560
	v_pk_fma_f32 v[38:39], v[88:89], v[14:15], v[38:39] op_sel:[0,0,0] op_sel_hi:[0,1,1]
	v_pk_fma_f32 v[40:41], v[88:89], v[16:17], v[40:41] op_sel:[1,0,0] op_sel_hi:[1,1,1]
	v_add_f32_dpp v22, v22, v22 quad_perm:[2,3,0,1] row_mask:0xf bank_mask:0xf
	v_add_f32_dpp v23, v23, v23 quad_perm:[2,3,0,1] row_mask:0xf bank_mask:0xf
	v_pk_fma_f32 v[42:43], v[90:91], v[18:19], v[42:43] op_sel:[0,0,0] op_sel_hi:[0,1,1]
	v_pk_fma_f32 v[44:45], v[90:91], v[20:21], v[44:45] op_sel:[1,0,0] op_sel_hi:[1,1,1]
	v_add_f32_dpp v22, v22, v22 row_half_mirror row_mask:0xf bank_mask:0xf
	v_add_f32_dpp v23, v23, v23 row_half_mirror row_mask:0xf bank_mask:0xf
	v_pk_fma_f32 v[6:7], v[60:61], v[22:23], v[30:31] op_sel:[0,0,0] op_sel_hi:[0,1,1] neg_lo:[0,1,0] neg_hi:[0,1,0]
	v_pk_fma_f32 v[8:9], v[60:61], v[22:23], v[32:33] op_sel:[1,0,0] op_sel_hi:[1,1,1] neg_lo:[0,1,0] neg_hi:[0,1,0]
	v_pk_mul_f32 v[26:27], v[6:7], v[76:77] op_sel:[0,0] op_sel_hi:[1,0]
	v_pk_fma_f32 v[10:11], v[62:63], v[22:23], v[34:35] op_sel:[0,0,0] op_sel_hi:[0,1,1] neg_lo:[0,1,0] neg_hi:[0,1,0]
	v_pk_fma_f32 v[26:27], v[8:9], v[76:77], v[26:27] op_sel:[0,1,0] op_sel_hi:[1,1,1]
	v_pk_fma_f32 v[12:13], v[62:63], v[22:23], v[36:37] op_sel:[1,0,0] op_sel_hi:[1,1,1] neg_lo:[0,1,0] neg_hi:[0,1,0]
	v_pk_fma_f32 v[26:27], v[10:11], v[78:79], v[26:27] op_sel:[0,0,0] op_sel_hi:[1,0,1]
	v_pk_fma_f32 v[14:15], v[64:65], v[22:23], v[38:39] op_sel:[0,0,0] op_sel_hi:[0,1,1] neg_lo:[0,1,0] neg_hi:[0,1,0]
	v_pk_fma_f32 v[26:27], v[12:13], v[78:79], v[26:27] op_sel:[0,1,0] op_sel_hi:[1,1,1]
	v_pk_fma_f32 v[16:17], v[64:65], v[22:23], v[40:41] op_sel:[1,0,0] op_sel_hi:[1,1,1] neg_lo:[0,1,0] neg_hi:[0,1,0]
	v_pk_fma_f32 v[26:27], v[14:15], v[80:81], v[26:27] op_sel:[0,0,0] op_sel_hi:[1,0,1]
	v_pk_fma_f32 v[18:19], v[66:67], v[22:23], v[42:43] op_sel:[0,0,0] op_sel_hi:[0,1,1] neg_lo:[0,1,0] neg_hi:[0,1,0]
	v_pk_fma_f32 v[26:27], v[16:17], v[80:81], v[26:27] op_sel:[0,1,0] op_sel_hi:[1,1,1]
	v_pk_fma_f32 v[20:21], v[66:67], v[22:23], v[44:45] op_sel:[1,0,0] op_sel_hi:[1,1,1] neg_lo:[0,1,0] neg_hi:[0,1,0]
	v_pk_fma_f32 v[26:27], v[18:19], v[82:83], v[26:27] op_sel:[0,0,0] op_sel_hi:[1,0,1]
	s_nop 0
	v_pk_fma_f32 v[26:27], v[20:21], v[82:83], v[26:27] op_sel:[0,1,0] op_sel_hi:[1,1,1]
	s_waitcnt lgkmcnt(0)
	v_pk_mul_f32 v[22:23], v[6:7], v[94:95] op_sel:[0,0] op_sel_hi:[1,0]
	v_pk_mul_f32 v[30:31], v[110:111], v[134:135] op_sel:[0,0] op_sel_hi:[0,1]
	ds_read_b128 v[52:55], v47 offset:512
	v_pk_fma_f32 v[22:23], v[8:9], v[94:95], v[22:23] op_sel:[0,1,0] op_sel_hi:[1,1,1]
	v_pk_mul_f32 v[32:33], v[110:111], v[134:135] op_sel:[1,0] op_sel_hi:[1,1]
	ds_read_b128 v[56:59], v47 offset:528
	v_pk_fma_f32 v[22:23], v[10:11], v[96:97], v[22:23] op_sel:[0,0,0] op_sel_hi:[1,0,1]
	v_pk_mul_f32 v[34:35], v[112:113], v[134:135] op_sel:[0,0] op_sel_hi:[0,1]
	ds_read_b128 v[68:71], v47 offset:8704
	v_pk_fma_f32 v[22:23], v[12:13], v[96:97], v[22:23] op_sel:[0,1,0] op_sel_hi:[1,1,1]
	v_pk_mul_f32 v[36:37], v[112:113], v[134:135] op_sel:[1,0] op_sel_hi:[1,1]
	ds_read_b128 v[72:75], v47 offset:8720
	v_pk_fma_f32 v[22:23], v[14:15], v[98:99], v[22:23] op_sel:[0,0,0] op_sel_hi:[1,0,1]
	v_pk_mul_f32 v[38:39], v[114:115], v[134:135] op_sel:[0,0] op_sel_hi:[0,1]
	ds_read_b64 v[92:93], v48 offset:512
	v_pk_fma_f32 v[22:23], v[16:17], v[98:99], v[22:23] op_sel:[0,1,0] op_sel_hi:[1,1,1]
	v_pk_mul_f32 v[40:41], v[114:115], v[134:135] op_sel:[1,0] op_sel_hi:[1,1]
	ds_read_b128 v[84:87], v47 offset:16896
	v_pk_fma_f32 v[22:23], v[18:19], v[100:101], v[22:23] op_sel:[0,0,0] op_sel_hi:[1,0,1]
	v_pk_mul_f32 v[42:43], v[116:117], v[134:135] op_sel:[0,0] op_sel_hi:[0,1]
	ds_read_b128 v[88:91], v47 offset:16912
	v_pk_fma_f32 v[22:23], v[20:21], v[100:101], v[22:23] op_sel:[0,1,0] op_sel_hi:[1,1,1]
	v_pk_mul_f32 v[44:45], v[116:117], v[134:135] op_sel:[1,0] op_sel_hi:[1,1]
	ds_read_b128 v[60:63], v47 offset:4608
	v_pk_fma_f32 v[30:31], v[126:127], v[6:7], v[30:31] op_sel:[0,0,0] op_sel_hi:[0,1,1]
	v_pk_fma_f32 v[32:33], v[126:127], v[8:9], v[32:33] op_sel:[1,0,0] op_sel_hi:[1,1,1]
	ds_read_b128 v[64:67], v47 offset:4624
	v_pk_fma_f32 v[34:35], v[128:129], v[10:11], v[34:35] op_sel:[0,0,0] op_sel_hi:[0,1,1]
	v_pk_fma_f32 v[36:37], v[128:129], v[12:13], v[36:37] op_sel:[1,0,0] op_sel_hi:[1,1,1]
	ds_read_b128 v[76:79], v47 offset:12800
	v_add_f32_dpp v22, v22, v22 quad_perm:[1,0,3,2] row_mask:0xf bank_mask:0xf
	v_add_f32_dpp v23, v23, v23 quad_perm:[1,0,3,2] row_mask:0xf bank_mask:0xf
	ds_read_b128 v[80:83], v47 offset:12816
	v_add_f32_dpp v26, v26, v26 quad_perm:[1,0,3,2] row_mask:0xf bank_mask:0xf
	v_add_f32_dpp v27, v27, v27 quad_perm:[1,0,3,2] row_mask:0xf bank_mask:0xf
	v_pk_fma_f32 v[38:39], v[130:131], v[14:15], v[38:39] op_sel:[0,0,0] op_sel_hi:[0,1,1]
	v_pk_fma_f32 v[40:41], v[130:131], v[16:17], v[40:41] op_sel:[1,0,0] op_sel_hi:[1,1,1]
	v_add_f32_dpp v22, v22, v22 quad_perm:[2,3,0,1] row_mask:0xf bank_mask:0xf
	v_add_f32_dpp v23, v23, v23 quad_perm:[2,3,0,1] row_mask:0xf bank_mask:0xf
	v_add_f32_dpp v26, v26, v26 quad_perm:[2,3,0,1] row_mask:0xf bank_mask:0xf
	v_add_f32_dpp v27, v27, v27 quad_perm:[2,3,0,1] row_mask:0xf bank_mask:0xf
	v_pk_fma_f32 v[42:43], v[132:133], v[18:19], v[42:43] op_sel:[0,0,0] op_sel_hi:[0,1,1]
	v_pk_fma_f32 v[44:45], v[132:133], v[20:21], v[44:45] op_sel:[1,0,0] op_sel_hi:[1,1,1]
	v_add_f32_dpp v22, v22, v22 row_half_mirror row_mask:0xf bank_mask:0xf
	v_add_f32_dpp v23, v23, v23 row_half_mirror row_mask:0xf bank_mask:0xf
	v_add_f32_dpp v26, v26, v26 row_half_mirror row_mask:0xf bank_mask:0xf
	v_add_f32_dpp v27, v27, v27 row_half_mirror row_mask:0xf bank_mask:0xf
	v_pk_fma_f32 v[6:7], v[102:103], v[22:23], v[30:31] op_sel:[0,0,0] op_sel_hi:[0,1,1] neg_lo:[0,1,0] neg_hi:[0,1,0]
	v_cvt_pk_f16_f32 v46, v26, v27
	v_pk_fma_f32 v[8:9], v[102:103], v[22:23], v[32:33] op_sel:[1,0,0] op_sel_hi:[1,1,1] neg_lo:[0,1,0] neg_hi:[0,1,0]
	v_pk_mul_f32 v[26:27], v[6:7], v[118:119] op_sel:[0,0] op_sel_hi:[1,0]
	v_pk_fma_f32 v[10:11], v[104:105], v[22:23], v[34:35] op_sel:[0,0,0] op_sel_hi:[0,1,1] neg_lo:[0,1,0] neg_hi:[0,1,0]
	v_pk_fma_f32 v[26:27], v[8:9], v[118:119], v[26:27] op_sel:[0,1,0] op_sel_hi:[1,1,1]
	v_pk_fma_f32 v[12:13], v[104:105], v[22:23], v[36:37] op_sel:[1,0,0] op_sel_hi:[1,1,1] neg_lo:[0,1,0] neg_hi:[0,1,0]
	v_pk_fma_f32 v[26:27], v[10:11], v[120:121], v[26:27] op_sel:[0,0,0] op_sel_hi:[1,0,1]
	v_pk_fma_f32 v[14:15], v[106:107], v[22:23], v[38:39] op_sel:[0,0,0] op_sel_hi:[0,1,1] neg_lo:[0,1,0] neg_hi:[0,1,0]
	v_pk_fma_f32 v[26:27], v[12:13], v[120:121], v[26:27] op_sel:[0,1,0] op_sel_hi:[1,1,1]
	v_pk_fma_f32 v[16:17], v[106:107], v[22:23], v[40:41] op_sel:[1,0,0] op_sel_hi:[1,1,1] neg_lo:[0,1,0] neg_hi:[0,1,0]
	v_pk_fma_f32 v[26:27], v[14:15], v[122:123], v[26:27] op_sel:[0,0,0] op_sel_hi:[1,0,1]
	v_pk_fma_f32 v[18:19], v[108:109], v[22:23], v[42:43] op_sel:[0,0,0] op_sel_hi:[0,1,1] neg_lo:[0,1,0] neg_hi:[0,1,0]
	v_pk_fma_f32 v[26:27], v[16:17], v[122:123], v[26:27] op_sel:[0,1,0] op_sel_hi:[1,1,1]
	v_pk_fma_f32 v[20:21], v[108:109], v[22:23], v[44:45] op_sel:[1,0,0] op_sel_hi:[1,1,1] neg_lo:[0,1,0] neg_hi:[0,1,0]
	v_pk_fma_f32 v[26:27], v[18:19], v[124:125], v[26:27] op_sel:[0,0,0] op_sel_hi:[1,0,1]
	ds_write_b32 v49, v46 offset:0
	v_pk_fma_f32 v[26:27], v[20:21], v[124:125], v[26:27] op_sel:[0,1,0] op_sel_hi:[1,1,1]
	s_waitcnt lgkmcnt(1)
	v_pk_mul_f32 v[22:23], v[6:7], v[52:53] op_sel:[0,0] op_sel_hi:[1,0]
	v_pk_mul_f32 v[30:31], v[68:69], v[92:93] op_sel:[0,0] op_sel_hi:[0,1]
	ds_read_b128 v[94:97], v47 offset:768
	v_pk_fma_f32 v[22:23], v[8:9], v[52:53], v[22:23] op_sel:[0,1,0] op_sel_hi:[1,1,1]
	v_pk_mul_f32 v[32:33], v[68:69], v[92:93] op_sel:[1,0] op_sel_hi:[1,1]
	ds_read_b128 v[98:101], v47 offset:784
	v_pk_fma_f32 v[22:23], v[10:11], v[54:55], v[22:23] op_sel:[0,0,0] op_sel_hi:[1,0,1]
	v_pk_mul_f32 v[34:35], v[70:71], v[92:93] op_sel:[0,0] op_sel_hi:[0,1]
	ds_read_b128 v[110:113], v47 offset:8960
	v_pk_fma_f32 v[22:23], v[12:13], v[54:55], v[22:23] op_sel:[0,1,0] op_sel_hi:[1,1,1]
	v_pk_mul_f32 v[36:37], v[70:71], v[92:93] op_sel:[1,0] op_sel_hi:[1,1]
	ds_read_b128 v[114:117], v47 offset:8976
	v_pk_fma_f32 v[22:23], v[14:15], v[56:57], v[22:23] op_sel:[0,0,0] op_sel_hi:[1,0,1]
	v_pk_mul_f32 v[38:39], v[72:73], v[92:93] op_sel:[0,0] op_sel_hi:[0,1]
	ds_read_b64 v[134:135], v48 offset:768
	v_pk_fma_f32 v[22:23], v[16:17], v[56:57], v[22:23] op_sel:[0,1,0] op_sel_hi:[1,1,1]
	v_pk_mul_f32 v[40:41], v[72:73], v[92:93] op_sel:[1,0] op_sel_hi:[1,1]
	ds_read_b128 v[126:129], v47 offset:17152
	v_pk_fma_f32 v[22:23], v[18:19], v[58:59], v[22:23] op_sel:[0,0,0] op_sel_hi:[1,0,1]
	v_pk_mul_f32 v[42:43], v[74:75], v[92:93] op_sel:[0,0] op_sel_hi:[0,1]
	ds_read_b128 v[130:133], v47 offset:17168
	v_pk_fma_f32 v[22:23], v[20:21], v[58:59], v[22:23] op_sel:[0,1,0] op_sel_hi:[1,1,1]
	v_pk_mul_f32 v[44:45], v[74:75], v[92:93] op_sel:[1,0] op_sel_hi:[1,1]
	ds_read_b128 v[102:105], v47 offset:4864
	v_pk_fma_f32 v[30:31], v[84:85], v[6:7], v[30:31] op_sel:[0,0,0] op_sel_hi:[0,1,1]
	v_pk_fma_f32 v[32:33], v[84:85], v[8:9], v[32:33] op_sel:[1,0,0] op_sel_hi:[1,1,1]
	ds_read_b128 v[106:109], v47 offset:4880
	v_pk_fma_f32 v[34:35], v[86:87], v[10:11], v[34:35] op_sel:[0,0,0] op_sel_hi:[0,1,1]
	v_pk_fma_f32 v[36:37], v[86:87], v[12:13], v[36:37] op_sel:[1,0,0] op_sel_hi:[1,1,1]
	ds_read_b128 v[118:121], v47 offset:13056
	v_add_f32_dpp v22, v22, v22 quad_perm:[1,0,3,2] row_mask:0xf bank_mask:0xf
	v_add_f32_dpp v23, v23, v23 quad_perm:[1,0,3,2] row_mask:0xf bank_mask:0xf
	ds_read_b128 v[122:125], v47 offset:13072
	v_add_f32_dpp v26, v26, v26 quad_perm:[1,0,3,2] row_mask:0xf bank_mask:0xf
	v_add_f32_dpp v27, v27, v27 quad_perm:[1,0,3,2] row_mask:0xf bank_mask:0xf
	v_pk_fma_f32 v[38:39], v[88:89], v[14:15], v[38:39] op_sel:[0,0,0] op_sel_hi:[0,1,1]
	v_pk_fma_f32 v[40:41], v[88:89], v[16:17], v[40:41] op_sel:[1,0,0] op_sel_hi:[1,1,1]
	v_add_f32_dpp v22, v22, v22 quad_perm:[2,3,0,1] row_mask:0xf bank_mask:0xf
	v_add_f32_dpp v23, v23, v23 quad_perm:[2,3,0,1] row_mask:0xf bank_mask:0xf
	v_add_f32_dpp v26, v26, v26 quad_perm:[2,3,0,1] row_mask:0xf bank_mask:0xf
	v_add_f32_dpp v27, v27, v27 quad_perm:[2,3,0,1] row_mask:0xf bank_mask:0xf
	v_pk_fma_f32 v[42:43], v[90:91], v[18:19], v[42:43] op_sel:[0,0,0] op_sel_hi:[0,1,1]
	v_pk_fma_f32 v[44:45], v[90:91], v[20:21], v[44:45] op_sel:[1,0,0] op_sel_hi:[1,1,1]
	v_add_f32_dpp v22, v22, v22 row_half_mirror row_mask:0xf bank_mask:0xf
	v_add_f32_dpp v23, v23, v23 row_half_mirror row_mask:0xf bank_mask:0xf
	v_add_f32_dpp v26, v26, v26 row_half_mirror row_mask:0xf bank_mask:0xf
	v_add_f32_dpp v27, v27, v27 row_half_mirror row_mask:0xf bank_mask:0xf
	v_pk_fma_f32 v[6:7], v[60:61], v[22:23], v[30:31] op_sel:[0,0,0] op_sel_hi:[0,1,1] neg_lo:[0,1,0] neg_hi:[0,1,0]
	v_cvt_pk_f16_f32 v46, v26, v27
	v_pk_fma_f32 v[8:9], v[60:61], v[22:23], v[32:33] op_sel:[1,0,0] op_sel_hi:[1,1,1] neg_lo:[0,1,0] neg_hi:[0,1,0]
	v_pk_mul_f32 v[26:27], v[6:7], v[76:77] op_sel:[0,0] op_sel_hi:[1,0]
	v_pk_fma_f32 v[10:11], v[62:63], v[22:23], v[34:35] op_sel:[0,0,0] op_sel_hi:[0,1,1] neg_lo:[0,1,0] neg_hi:[0,1,0]
	v_pk_fma_f32 v[26:27], v[8:9], v[76:77], v[26:27] op_sel:[0,1,0] op_sel_hi:[1,1,1]
	v_pk_fma_f32 v[12:13], v[62:63], v[22:23], v[36:37] op_sel:[1,0,0] op_sel_hi:[1,1,1] neg_lo:[0,1,0] neg_hi:[0,1,0]
	v_pk_fma_f32 v[26:27], v[10:11], v[78:79], v[26:27] op_sel:[0,0,0] op_sel_hi:[1,0,1]
	v_pk_fma_f32 v[14:15], v[64:65], v[22:23], v[38:39] op_sel:[0,0,0] op_sel_hi:[0,1,1] neg_lo:[0,1,0] neg_hi:[0,1,0]
	v_pk_fma_f32 v[26:27], v[12:13], v[78:79], v[26:27] op_sel:[0,1,0] op_sel_hi:[1,1,1]
	v_pk_fma_f32 v[16:17], v[64:65], v[22:23], v[40:41] op_sel:[1,0,0] op_sel_hi:[1,1,1] neg_lo:[0,1,0] neg_hi:[0,1,0]
	v_pk_fma_f32 v[26:27], v[14:15], v[80:81], v[26:27] op_sel:[0,0,0] op_sel_hi:[1,0,1]
	v_pk_fma_f32 v[18:19], v[66:67], v[22:23], v[42:43] op_sel:[0,0,0] op_sel_hi:[0,1,1] neg_lo:[0,1,0] neg_hi:[0,1,0]
	v_pk_fma_f32 v[26:27], v[16:17], v[80:81], v[26:27] op_sel:[0,1,0] op_sel_hi:[1,1,1]
	v_pk_fma_f32 v[20:21], v[66:67], v[22:23], v[44:45] op_sel:[1,0,0] op_sel_hi:[1,1,1] neg_lo:[0,1,0] neg_hi:[0,1,0]
	v_pk_fma_f32 v[26:27], v[18:19], v[82:83], v[26:27] op_sel:[0,0,0] op_sel_hi:[1,0,1]
	ds_write_b32 v49, v46 offset:128
	v_pk_fma_f32 v[26:27], v[20:21], v[82:83], v[26:27] op_sel:[0,1,0] op_sel_hi:[1,1,1]
	s_waitcnt lgkmcnt(1)
	v_pk_mul_f32 v[22:23], v[6:7], v[94:95] op_sel:[0,0] op_sel_hi:[1,0]
	v_pk_mul_f32 v[30:31], v[110:111], v[134:135] op_sel:[0,0] op_sel_hi:[0,1]
	ds_read_b128 v[52:55], v47 offset:1024
	v_pk_fma_f32 v[22:23], v[8:9], v[94:95], v[22:23] op_sel:[0,1,0] op_sel_hi:[1,1,1]
	v_pk_mul_f32 v[32:33], v[110:111], v[134:135] op_sel:[1,0] op_sel_hi:[1,1]
	ds_read_b128 v[56:59], v47 offset:1040
	v_pk_fma_f32 v[22:23], v[10:11], v[96:97], v[22:23] op_sel:[0,0,0] op_sel_hi:[1,0,1]
	v_pk_mul_f32 v[34:35], v[112:113], v[134:135] op_sel:[0,0] op_sel_hi:[0,1]
	ds_read_b128 v[68:71], v47 offset:9216
	v_pk_fma_f32 v[22:23], v[12:13], v[96:97], v[22:23] op_sel:[0,1,0] op_sel_hi:[1,1,1]
	v_pk_mul_f32 v[36:37], v[112:113], v[134:135] op_sel:[1,0] op_sel_hi:[1,1]
	ds_read_b128 v[72:75], v47 offset:9232
	v_pk_fma_f32 v[22:23], v[14:15], v[98:99], v[22:23] op_sel:[0,0,0] op_sel_hi:[1,0,1]
	v_pk_mul_f32 v[38:39], v[114:115], v[134:135] op_sel:[0,0] op_sel_hi:[0,1]
	ds_read_b64 v[92:93], v48 offset:1024
	v_pk_fma_f32 v[22:23], v[16:17], v[98:99], v[22:23] op_sel:[0,1,0] op_sel_hi:[1,1,1]
	v_pk_mul_f32 v[40:41], v[114:115], v[134:135] op_sel:[1,0] op_sel_hi:[1,1]
	ds_read_b128 v[84:87], v47 offset:17408
	v_pk_fma_f32 v[22:23], v[18:19], v[100:101], v[22:23] op_sel:[0,0,0] op_sel_hi:[1,0,1]
	v_pk_mul_f32 v[42:43], v[116:117], v[134:135] op_sel:[0,0] op_sel_hi:[0,1]
	ds_read_b128 v[88:91], v47 offset:17424
	v_pk_fma_f32 v[22:23], v[20:21], v[100:101], v[22:23] op_sel:[0,1,0] op_sel_hi:[1,1,1]
	v_pk_mul_f32 v[44:45], v[116:117], v[134:135] op_sel:[1,0] op_sel_hi:[1,1]
	ds_read_b128 v[60:63], v47 offset:5120
	v_pk_fma_f32 v[30:31], v[126:127], v[6:7], v[30:31] op_sel:[0,0,0] op_sel_hi:[0,1,1]
	v_pk_fma_f32 v[32:33], v[126:127], v[8:9], v[32:33] op_sel:[1,0,0] op_sel_hi:[1,1,1]
	ds_read_b128 v[64:67], v47 offset:5136
	v_pk_fma_f32 v[34:35], v[128:129], v[10:11], v[34:35] op_sel:[0,0,0] op_sel_hi:[0,1,1]
	v_pk_fma_f32 v[36:37], v[128:129], v[12:13], v[36:37] op_sel:[1,0,0] op_sel_hi:[1,1,1]
	ds_read_b128 v[76:79], v47 offset:13312
	v_add_f32_dpp v22, v22, v22 quad_perm:[1,0,3,2] row_mask:0xf bank_mask:0xf
	v_add_f32_dpp v23, v23, v23 quad_perm:[1,0,3,2] row_mask:0xf bank_mask:0xf
	ds_read_b128 v[80:83], v47 offset:13328
	v_add_f32_dpp v26, v26, v26 quad_perm:[1,0,3,2] row_mask:0xf bank_mask:0xf
	v_add_f32_dpp v27, v27, v27 quad_perm:[1,0,3,2] row_mask:0xf bank_mask:0xf
	v_pk_fma_f32 v[38:39], v[130:131], v[14:15], v[38:39] op_sel:[0,0,0] op_sel_hi:[0,1,1]
	v_pk_fma_f32 v[40:41], v[130:131], v[16:17], v[40:41] op_sel:[1,0,0] op_sel_hi:[1,1,1]
	v_add_f32_dpp v22, v22, v22 quad_perm:[2,3,0,1] row_mask:0xf bank_mask:0xf
	v_add_f32_dpp v23, v23, v23 quad_perm:[2,3,0,1] row_mask:0xf bank_mask:0xf
	v_add_f32_dpp v26, v26, v26 quad_perm:[2,3,0,1] row_mask:0xf bank_mask:0xf
	v_add_f32_dpp v27, v27, v27 quad_perm:[2,3,0,1] row_mask:0xf bank_mask:0xf
	v_pk_fma_f32 v[42:43], v[132:133], v[18:19], v[42:43] op_sel:[0,0,0] op_sel_hi:[0,1,1]
	v_pk_fma_f32 v[44:45], v[132:133], v[20:21], v[44:45] op_sel:[1,0,0] op_sel_hi:[1,1,1]
	v_add_f32_dpp v22, v22, v22 row_half_mirror row_mask:0xf bank_mask:0xf
	v_add_f32_dpp v23, v23, v23 row_half_mirror row_mask:0xf bank_mask:0xf
	v_add_f32_dpp v26, v26, v26 row_half_mirror row_mask:0xf bank_mask:0xf
	v_add_f32_dpp v27, v27, v27 row_half_mirror row_mask:0xf bank_mask:0xf
	v_pk_fma_f32 v[6:7], v[102:103], v[22:23], v[30:31] op_sel:[0,0,0] op_sel_hi:[0,1,1] neg_lo:[0,1,0] neg_hi:[0,1,0]
	v_cvt_pk_f16_f32 v46, v26, v27
	v_pk_fma_f32 v[8:9], v[102:103], v[22:23], v[32:33] op_sel:[1,0,0] op_sel_hi:[1,1,1] neg_lo:[0,1,0] neg_hi:[0,1,0]
	v_pk_mul_f32 v[26:27], v[6:7], v[118:119] op_sel:[0,0] op_sel_hi:[1,0]
	v_pk_fma_f32 v[10:11], v[104:105], v[22:23], v[34:35] op_sel:[0,0,0] op_sel_hi:[0,1,1] neg_lo:[0,1,0] neg_hi:[0,1,0]
	v_pk_fma_f32 v[26:27], v[8:9], v[118:119], v[26:27] op_sel:[0,1,0] op_sel_hi:[1,1,1]
	v_pk_fma_f32 v[12:13], v[104:105], v[22:23], v[36:37] op_sel:[1,0,0] op_sel_hi:[1,1,1] neg_lo:[0,1,0] neg_hi:[0,1,0]
	v_pk_fma_f32 v[26:27], v[10:11], v[120:121], v[26:27] op_sel:[0,0,0] op_sel_hi:[1,0,1]
	v_pk_fma_f32 v[14:15], v[106:107], v[22:23], v[38:39] op_sel:[0,0,0] op_sel_hi:[0,1,1] neg_lo:[0,1,0] neg_hi:[0,1,0]
	v_pk_fma_f32 v[26:27], v[12:13], v[120:121], v[26:27] op_sel:[0,1,0] op_sel_hi:[1,1,1]
	v_pk_fma_f32 v[16:17], v[106:107], v[22:23], v[40:41] op_sel:[1,0,0] op_sel_hi:[1,1,1] neg_lo:[0,1,0] neg_hi:[0,1,0]
	v_pk_fma_f32 v[26:27], v[14:15], v[122:123], v[26:27] op_sel:[0,0,0] op_sel_hi:[1,0,1]
	v_pk_fma_f32 v[18:19], v[108:109], v[22:23], v[42:43] op_sel:[0,0,0] op_sel_hi:[0,1,1] neg_lo:[0,1,0] neg_hi:[0,1,0]
	v_pk_fma_f32 v[26:27], v[16:17], v[122:123], v[26:27] op_sel:[0,1,0] op_sel_hi:[1,1,1]
	v_pk_fma_f32 v[20:21], v[108:109], v[22:23], v[44:45] op_sel:[1,0,0] op_sel_hi:[1,1,1] neg_lo:[0,1,0] neg_hi:[0,1,0]
	v_pk_fma_f32 v[26:27], v[18:19], v[124:125], v[26:27] op_sel:[0,0,0] op_sel_hi:[1,0,1]
	ds_write_b32 v49, v46 offset:256
	v_pk_fma_f32 v[26:27], v[20:21], v[124:125], v[26:27] op_sel:[0,1,0] op_sel_hi:[1,1,1]
	s_waitcnt lgkmcnt(1)
	v_pk_mul_f32 v[22:23], v[6:7], v[52:53] op_sel:[0,0] op_sel_hi:[1,0]
	v_pk_mul_f32 v[30:31], v[68:69], v[92:93] op_sel:[0,0] op_sel_hi:[0,1]
	ds_read_b128 v[94:97], v47 offset:1280
	v_pk_fma_f32 v[22:23], v[8:9], v[52:53], v[22:23] op_sel:[0,1,0] op_sel_hi:[1,1,1]
	v_pk_mul_f32 v[32:33], v[68:69], v[92:93] op_sel:[1,0] op_sel_hi:[1,1]
	ds_read_b128 v[98:101], v47 offset:1296
	v_pk_fma_f32 v[22:23], v[10:11], v[54:55], v[22:23] op_sel:[0,0,0] op_sel_hi:[1,0,1]
	v_pk_mul_f32 v[34:35], v[70:71], v[92:93] op_sel:[0,0] op_sel_hi:[0,1]
	ds_read_b128 v[110:113], v47 offset:9472
	v_pk_fma_f32 v[22:23], v[12:13], v[54:55], v[22:23] op_sel:[0,1,0] op_sel_hi:[1,1,1]
	v_pk_mul_f32 v[36:37], v[70:71], v[92:93] op_sel:[1,0] op_sel_hi:[1,1]
	ds_read_b128 v[114:117], v47 offset:9488
	v_pk_fma_f32 v[22:23], v[14:15], v[56:57], v[22:23] op_sel:[0,0,0] op_sel_hi:[1,0,1]
	v_pk_mul_f32 v[38:39], v[72:73], v[92:93] op_sel:[0,0] op_sel_hi:[0,1]
	ds_read_b64 v[134:135], v48 offset:1280
	v_pk_fma_f32 v[22:23], v[16:17], v[56:57], v[22:23] op_sel:[0,1,0] op_sel_hi:[1,1,1]
	v_pk_mul_f32 v[40:41], v[72:73], v[92:93] op_sel:[1,0] op_sel_hi:[1,1]
	ds_read_b128 v[126:129], v47 offset:17664
	v_pk_fma_f32 v[22:23], v[18:19], v[58:59], v[22:23] op_sel:[0,0,0] op_sel_hi:[1,0,1]
	v_pk_mul_f32 v[42:43], v[74:75], v[92:93] op_sel:[0,0] op_sel_hi:[0,1]
	ds_read_b128 v[130:133], v47 offset:17680
	v_pk_fma_f32 v[22:23], v[20:21], v[58:59], v[22:23] op_sel:[0,1,0] op_sel_hi:[1,1,1]
	v_pk_mul_f32 v[44:45], v[74:75], v[92:93] op_sel:[1,0] op_sel_hi:[1,1]
	ds_read_b128 v[102:105], v47 offset:5376
	v_pk_fma_f32 v[30:31], v[84:85], v[6:7], v[30:31] op_sel:[0,0,0] op_sel_hi:[0,1,1]
	v_pk_fma_f32 v[32:33], v[84:85], v[8:9], v[32:33] op_sel:[1,0,0] op_sel_hi:[1,1,1]
	ds_read_b128 v[106:109], v47 offset:5392
	v_pk_fma_f32 v[34:35], v[86:87], v[10:11], v[34:35] op_sel:[0,0,0] op_sel_hi:[0,1,1]
	v_pk_fma_f32 v[36:37], v[86:87], v[12:13], v[36:37] op_sel:[1,0,0] op_sel_hi:[1,1,1]
	ds_read_b128 v[118:121], v47 offset:13568
	v_add_f32_dpp v22, v22, v22 quad_perm:[1,0,3,2] row_mask:0xf bank_mask:0xf
	v_add_f32_dpp v23, v23, v23 quad_perm:[1,0,3,2] row_mask:0xf bank_mask:0xf
	ds_read_b128 v[122:125], v47 offset:13584
	v_add_f32_dpp v26, v26, v26 quad_perm:[1,0,3,2] row_mask:0xf bank_mask:0xf
	v_add_f32_dpp v27, v27, v27 quad_perm:[1,0,3,2] row_mask:0xf bank_mask:0xf
	v_pk_fma_f32 v[38:39], v[88:89], v[14:15], v[38:39] op_sel:[0,0,0] op_sel_hi:[0,1,1]
	v_pk_fma_f32 v[40:41], v[88:89], v[16:17], v[40:41] op_sel:[1,0,0] op_sel_hi:[1,1,1]
	v_add_f32_dpp v22, v22, v22 quad_perm:[2,3,0,1] row_mask:0xf bank_mask:0xf
	v_add_f32_dpp v23, v23, v23 quad_perm:[2,3,0,1] row_mask:0xf bank_mask:0xf
	v_add_f32_dpp v26, v26, v26 quad_perm:[2,3,0,1] row_mask:0xf bank_mask:0xf
	v_add_f32_dpp v27, v27, v27 quad_perm:[2,3,0,1] row_mask:0xf bank_mask:0xf
	v_pk_fma_f32 v[42:43], v[90:91], v[18:19], v[42:43] op_sel:[0,0,0] op_sel_hi:[0,1,1]
	v_pk_fma_f32 v[44:45], v[90:91], v[20:21], v[44:45] op_sel:[1,0,0] op_sel_hi:[1,1,1]
	v_add_f32_dpp v22, v22, v22 row_half_mirror row_mask:0xf bank_mask:0xf
	v_add_f32_dpp v23, v23, v23 row_half_mirror row_mask:0xf bank_mask:0xf
	v_add_f32_dpp v26, v26, v26 row_half_mirror row_mask:0xf bank_mask:0xf
	v_add_f32_dpp v27, v27, v27 row_half_mirror row_mask:0xf bank_mask:0xf
	v_pk_fma_f32 v[6:7], v[60:61], v[22:23], v[30:31] op_sel:[0,0,0] op_sel_hi:[0,1,1] neg_lo:[0,1,0] neg_hi:[0,1,0]
	v_cvt_pk_f16_f32 v46, v26, v27
	v_pk_fma_f32 v[8:9], v[60:61], v[22:23], v[32:33] op_sel:[1,0,0] op_sel_hi:[1,1,1] neg_lo:[0,1,0] neg_hi:[0,1,0]
	v_pk_mul_f32 v[26:27], v[6:7], v[76:77] op_sel:[0,0] op_sel_hi:[1,0]
	v_pk_fma_f32 v[10:11], v[62:63], v[22:23], v[34:35] op_sel:[0,0,0] op_sel_hi:[0,1,1] neg_lo:[0,1,0] neg_hi:[0,1,0]
	v_pk_fma_f32 v[26:27], v[8:9], v[76:77], v[26:27] op_sel:[0,1,0] op_sel_hi:[1,1,1]
	v_pk_fma_f32 v[12:13], v[62:63], v[22:23], v[36:37] op_sel:[1,0,0] op_sel_hi:[1,1,1] neg_lo:[0,1,0] neg_hi:[0,1,0]
	v_pk_fma_f32 v[26:27], v[10:11], v[78:79], v[26:27] op_sel:[0,0,0] op_sel_hi:[1,0,1]
	v_pk_fma_f32 v[14:15], v[64:65], v[22:23], v[38:39] op_sel:[0,0,0] op_sel_hi:[0,1,1] neg_lo:[0,1,0] neg_hi:[0,1,0]
	v_pk_fma_f32 v[26:27], v[12:13], v[78:79], v[26:27] op_sel:[0,1,0] op_sel_hi:[1,1,1]
	v_pk_fma_f32 v[16:17], v[64:65], v[22:23], v[40:41] op_sel:[1,0,0] op_sel_hi:[1,1,1] neg_lo:[0,1,0] neg_hi:[0,1,0]
	v_pk_fma_f32 v[26:27], v[14:15], v[80:81], v[26:27] op_sel:[0,0,0] op_sel_hi:[1,0,1]
	v_pk_fma_f32 v[18:19], v[66:67], v[22:23], v[42:43] op_sel:[0,0,0] op_sel_hi:[0,1,1] neg_lo:[0,1,0] neg_hi:[0,1,0]
	v_pk_fma_f32 v[26:27], v[16:17], v[80:81], v[26:27] op_sel:[0,1,0] op_sel_hi:[1,1,1]
	v_pk_fma_f32 v[20:21], v[66:67], v[22:23], v[44:45] op_sel:[1,0,0] op_sel_hi:[1,1,1] neg_lo:[0,1,0] neg_hi:[0,1,0]
	v_pk_fma_f32 v[26:27], v[18:19], v[82:83], v[26:27] op_sel:[0,0,0] op_sel_hi:[1,0,1]
	ds_write_b32 v49, v46 offset:384
	v_pk_fma_f32 v[26:27], v[20:21], v[82:83], v[26:27] op_sel:[0,1,0] op_sel_hi:[1,1,1]
	s_waitcnt lgkmcnt(1)
	v_pk_mul_f32 v[22:23], v[6:7], v[94:95] op_sel:[0,0] op_sel_hi:[1,0]
	v_pk_mul_f32 v[30:31], v[110:111], v[134:135] op_sel:[0,0] op_sel_hi:[0,1]
	ds_read_b128 v[52:55], v47 offset:1536
	v_pk_fma_f32 v[22:23], v[8:9], v[94:95], v[22:23] op_sel:[0,1,0] op_sel_hi:[1,1,1]
	v_pk_mul_f32 v[32:33], v[110:111], v[134:135] op_sel:[1,0] op_sel_hi:[1,1]
	ds_read_b128 v[56:59], v47 offset:1552
	v_pk_fma_f32 v[22:23], v[10:11], v[96:97], v[22:23] op_sel:[0,0,0] op_sel_hi:[1,0,1]
	v_pk_mul_f32 v[34:35], v[112:113], v[134:135] op_sel:[0,0] op_sel_hi:[0,1]
	ds_read_b128 v[68:71], v47 offset:9728
	v_pk_fma_f32 v[22:23], v[12:13], v[96:97], v[22:23] op_sel:[0,1,0] op_sel_hi:[1,1,1]
	v_pk_mul_f32 v[36:37], v[112:113], v[134:135] op_sel:[1,0] op_sel_hi:[1,1]
	ds_read_b128 v[72:75], v47 offset:9744
	v_pk_fma_f32 v[22:23], v[14:15], v[98:99], v[22:23] op_sel:[0,0,0] op_sel_hi:[1,0,1]
	v_pk_mul_f32 v[38:39], v[114:115], v[134:135] op_sel:[0,0] op_sel_hi:[0,1]
	ds_read_b64 v[92:93], v48 offset:1536
	v_pk_fma_f32 v[22:23], v[16:17], v[98:99], v[22:23] op_sel:[0,1,0] op_sel_hi:[1,1,1]
	v_pk_mul_f32 v[40:41], v[114:115], v[134:135] op_sel:[1,0] op_sel_hi:[1,1]
	ds_read_b128 v[84:87], v47 offset:17920
	v_pk_fma_f32 v[22:23], v[18:19], v[100:101], v[22:23] op_sel:[0,0,0] op_sel_hi:[1,0,1]
	v_pk_mul_f32 v[42:43], v[116:117], v[134:135] op_sel:[0,0] op_sel_hi:[0,1]
	ds_read_b128 v[88:91], v47 offset:17936
	v_pk_fma_f32 v[22:23], v[20:21], v[100:101], v[22:23] op_sel:[0,1,0] op_sel_hi:[1,1,1]
	v_pk_mul_f32 v[44:45], v[116:117], v[134:135] op_sel:[1,0] op_sel_hi:[1,1]
	ds_read_b128 v[60:63], v47 offset:5632
	v_pk_fma_f32 v[30:31], v[126:127], v[6:7], v[30:31] op_sel:[0,0,0] op_sel_hi:[0,1,1]
	v_pk_fma_f32 v[32:33], v[126:127], v[8:9], v[32:33] op_sel:[1,0,0] op_sel_hi:[1,1,1]
	ds_read_b128 v[64:67], v47 offset:5648
	v_pk_fma_f32 v[34:35], v[128:129], v[10:11], v[34:35] op_sel:[0,0,0] op_sel_hi:[0,1,1]
	v_pk_fma_f32 v[36:37], v[128:129], v[12:13], v[36:37] op_sel:[1,0,0] op_sel_hi:[1,1,1]
	ds_read_b128 v[76:79], v47 offset:13824
	v_add_f32_dpp v22, v22, v22 quad_perm:[1,0,3,2] row_mask:0xf bank_mask:0xf
	v_add_f32_dpp v23, v23, v23 quad_perm:[1,0,3,2] row_mask:0xf bank_mask:0xf
	ds_read_b128 v[80:83], v47 offset:13840
	v_add_f32_dpp v26, v26, v26 quad_perm:[1,0,3,2] row_mask:0xf bank_mask:0xf
	v_add_f32_dpp v27, v27, v27 quad_perm:[1,0,3,2] row_mask:0xf bank_mask:0xf
	v_pk_fma_f32 v[38:39], v[130:131], v[14:15], v[38:39] op_sel:[0,0,0] op_sel_hi:[0,1,1]
	v_pk_fma_f32 v[40:41], v[130:131], v[16:17], v[40:41] op_sel:[1,0,0] op_sel_hi:[1,1,1]
	v_add_f32_dpp v22, v22, v22 quad_perm:[2,3,0,1] row_mask:0xf bank_mask:0xf
	v_add_f32_dpp v23, v23, v23 quad_perm:[2,3,0,1] row_mask:0xf bank_mask:0xf
	v_add_f32_dpp v26, v26, v26 quad_perm:[2,3,0,1] row_mask:0xf bank_mask:0xf
	v_add_f32_dpp v27, v27, v27 quad_perm:[2,3,0,1] row_mask:0xf bank_mask:0xf
	v_pk_fma_f32 v[42:43], v[132:133], v[18:19], v[42:43] op_sel:[0,0,0] op_sel_hi:[0,1,1]
	v_pk_fma_f32 v[44:45], v[132:133], v[20:21], v[44:45] op_sel:[1,0,0] op_sel_hi:[1,1,1]
	v_add_f32_dpp v22, v22, v22 row_half_mirror row_mask:0xf bank_mask:0xf
	v_add_f32_dpp v23, v23, v23 row_half_mirror row_mask:0xf bank_mask:0xf
	v_add_f32_dpp v26, v26, v26 row_half_mirror row_mask:0xf bank_mask:0xf
	v_add_f32_dpp v27, v27, v27 row_half_mirror row_mask:0xf bank_mask:0xf
	v_pk_fma_f32 v[6:7], v[102:103], v[22:23], v[30:31] op_sel:[0,0,0] op_sel_hi:[0,1,1] neg_lo:[0,1,0] neg_hi:[0,1,0]
	v_cvt_pk_f16_f32 v46, v26, v27
	v_pk_fma_f32 v[8:9], v[102:103], v[22:23], v[32:33] op_sel:[1,0,0] op_sel_hi:[1,1,1] neg_lo:[0,1,0] neg_hi:[0,1,0]
	v_pk_mul_f32 v[26:27], v[6:7], v[118:119] op_sel:[0,0] op_sel_hi:[1,0]
	v_pk_fma_f32 v[10:11], v[104:105], v[22:23], v[34:35] op_sel:[0,0,0] op_sel_hi:[0,1,1] neg_lo:[0,1,0] neg_hi:[0,1,0]
	v_pk_fma_f32 v[26:27], v[8:9], v[118:119], v[26:27] op_sel:[0,1,0] op_sel_hi:[1,1,1]
	v_pk_fma_f32 v[12:13], v[104:105], v[22:23], v[36:37] op_sel:[1,0,0] op_sel_hi:[1,1,1] neg_lo:[0,1,0] neg_hi:[0,1,0]
	v_pk_fma_f32 v[26:27], v[10:11], v[120:121], v[26:27] op_sel:[0,0,0] op_sel_hi:[1,0,1]
	v_pk_fma_f32 v[14:15], v[106:107], v[22:23], v[38:39] op_sel:[0,0,0] op_sel_hi:[0,1,1] neg_lo:[0,1,0] neg_hi:[0,1,0]
	v_pk_fma_f32 v[26:27], v[12:13], v[120:121], v[26:27] op_sel:[0,1,0] op_sel_hi:[1,1,1]
	v_pk_fma_f32 v[16:17], v[106:107], v[22:23], v[40:41] op_sel:[1,0,0] op_sel_hi:[1,1,1] neg_lo:[0,1,0] neg_hi:[0,1,0]
	v_pk_fma_f32 v[26:27], v[14:15], v[122:123], v[26:27] op_sel:[0,0,0] op_sel_hi:[1,0,1]
	v_pk_fma_f32 v[18:19], v[108:109], v[22:23], v[42:43] op_sel:[0,0,0] op_sel_hi:[0,1,1] neg_lo:[0,1,0] neg_hi:[0,1,0]
	v_pk_fma_f32 v[26:27], v[16:17], v[122:123], v[26:27] op_sel:[0,1,0] op_sel_hi:[1,1,1]
	v_pk_fma_f32 v[20:21], v[108:109], v[22:23], v[44:45] op_sel:[1,0,0] op_sel_hi:[1,1,1] neg_lo:[0,1,0] neg_hi:[0,1,0]
	v_pk_fma_f32 v[26:27], v[18:19], v[124:125], v[26:27] op_sel:[0,0,0] op_sel_hi:[1,0,1]
	ds_write_b32 v49, v46 offset:512
	v_pk_fma_f32 v[26:27], v[20:21], v[124:125], v[26:27] op_sel:[0,1,0] op_sel_hi:[1,1,1]
	s_waitcnt lgkmcnt(1)
	v_pk_mul_f32 v[22:23], v[6:7], v[52:53] op_sel:[0,0] op_sel_hi:[1,0]
	v_pk_mul_f32 v[30:31], v[68:69], v[92:93] op_sel:[0,0] op_sel_hi:[0,1]
	ds_read_b128 v[94:97], v47 offset:1792
	v_pk_fma_f32 v[22:23], v[8:9], v[52:53], v[22:23] op_sel:[0,1,0] op_sel_hi:[1,1,1]
	v_pk_mul_f32 v[32:33], v[68:69], v[92:93] op_sel:[1,0] op_sel_hi:[1,1]
	ds_read_b128 v[98:101], v47 offset:1808
	v_pk_fma_f32 v[22:23], v[10:11], v[54:55], v[22:23] op_sel:[0,0,0] op_sel_hi:[1,0,1]
	v_pk_mul_f32 v[34:35], v[70:71], v[92:93] op_sel:[0,0] op_sel_hi:[0,1]
	ds_read_b128 v[110:113], v47 offset:9984
	v_pk_fma_f32 v[22:23], v[12:13], v[54:55], v[22:23] op_sel:[0,1,0] op_sel_hi:[1,1,1]
	v_pk_mul_f32 v[36:37], v[70:71], v[92:93] op_sel:[1,0] op_sel_hi:[1,1]
	ds_read_b128 v[114:117], v47 offset:10000
	v_pk_fma_f32 v[22:23], v[14:15], v[56:57], v[22:23] op_sel:[0,0,0] op_sel_hi:[1,0,1]
	v_pk_mul_f32 v[38:39], v[72:73], v[92:93] op_sel:[0,0] op_sel_hi:[0,1]
	ds_read_b64 v[134:135], v48 offset:1792
	v_pk_fma_f32 v[22:23], v[16:17], v[56:57], v[22:23] op_sel:[0,1,0] op_sel_hi:[1,1,1]
	v_pk_mul_f32 v[40:41], v[72:73], v[92:93] op_sel:[1,0] op_sel_hi:[1,1]
	ds_read_b128 v[126:129], v47 offset:18176
	v_pk_fma_f32 v[22:23], v[18:19], v[58:59], v[22:23] op_sel:[0,0,0] op_sel_hi:[1,0,1]
	v_pk_mul_f32 v[42:43], v[74:75], v[92:93] op_sel:[0,0] op_sel_hi:[0,1]
	ds_read_b128 v[130:133], v47 offset:18192
	v_pk_fma_f32 v[22:23], v[20:21], v[58:59], v[22:23] op_sel:[0,1,0] op_sel_hi:[1,1,1]
	v_pk_mul_f32 v[44:45], v[74:75], v[92:93] op_sel:[1,0] op_sel_hi:[1,1]
	ds_read_b128 v[102:105], v47 offset:5888
	v_pk_fma_f32 v[30:31], v[84:85], v[6:7], v[30:31] op_sel:[0,0,0] op_sel_hi:[0,1,1]
	v_pk_fma_f32 v[32:33], v[84:85], v[8:9], v[32:33] op_sel:[1,0,0] op_sel_hi:[1,1,1]
	ds_read_b128 v[106:109], v47 offset:5904
	v_pk_fma_f32 v[34:35], v[86:87], v[10:11], v[34:35] op_sel:[0,0,0] op_sel_hi:[0,1,1]
	v_pk_fma_f32 v[36:37], v[86:87], v[12:13], v[36:37] op_sel:[1,0,0] op_sel_hi:[1,1,1]
	ds_read_b128 v[118:121], v47 offset:14080
	v_add_f32_dpp v22, v22, v22 quad_perm:[1,0,3,2] row_mask:0xf bank_mask:0xf
	v_add_f32_dpp v23, v23, v23 quad_perm:[1,0,3,2] row_mask:0xf bank_mask:0xf
	ds_read_b128 v[122:125], v47 offset:14096
	v_add_f32_dpp v26, v26, v26 quad_perm:[1,0,3,2] row_mask:0xf bank_mask:0xf
	v_add_f32_dpp v27, v27, v27 quad_perm:[1,0,3,2] row_mask:0xf bank_mask:0xf
	v_pk_fma_f32 v[38:39], v[88:89], v[14:15], v[38:39] op_sel:[0,0,0] op_sel_hi:[0,1,1]
	v_pk_fma_f32 v[40:41], v[88:89], v[16:17], v[40:41] op_sel:[1,0,0] op_sel_hi:[1,1,1]
	v_add_f32_dpp v22, v22, v22 quad_perm:[2,3,0,1] row_mask:0xf bank_mask:0xf
	v_add_f32_dpp v23, v23, v23 quad_perm:[2,3,0,1] row_mask:0xf bank_mask:0xf
	v_add_f32_dpp v26, v26, v26 quad_perm:[2,3,0,1] row_mask:0xf bank_mask:0xf
	v_add_f32_dpp v27, v27, v27 quad_perm:[2,3,0,1] row_mask:0xf bank_mask:0xf
	v_pk_fma_f32 v[42:43], v[90:91], v[18:19], v[42:43] op_sel:[0,0,0] op_sel_hi:[0,1,1]
	v_pk_fma_f32 v[44:45], v[90:91], v[20:21], v[44:45] op_sel:[1,0,0] op_sel_hi:[1,1,1]
	v_add_f32_dpp v22, v22, v22 row_half_mirror row_mask:0xf bank_mask:0xf
	v_add_f32_dpp v23, v23, v23 row_half_mirror row_mask:0xf bank_mask:0xf
	v_add_f32_dpp v26, v26, v26 row_half_mirror row_mask:0xf bank_mask:0xf
	v_add_f32_dpp v27, v27, v27 row_half_mirror row_mask:0xf bank_mask:0xf
	v_pk_fma_f32 v[6:7], v[60:61], v[22:23], v[30:31] op_sel:[0,0,0] op_sel_hi:[0,1,1] neg_lo:[0,1,0] neg_hi:[0,1,0]
	v_cvt_pk_f16_f32 v46, v26, v27
	v_pk_fma_f32 v[8:9], v[60:61], v[22:23], v[32:33] op_sel:[1,0,0] op_sel_hi:[1,1,1] neg_lo:[0,1,0] neg_hi:[0,1,0]
	v_pk_mul_f32 v[26:27], v[6:7], v[76:77] op_sel:[0,0] op_sel_hi:[1,0]
	v_pk_fma_f32 v[10:11], v[62:63], v[22:23], v[34:35] op_sel:[0,0,0] op_sel_hi:[0,1,1] neg_lo:[0,1,0] neg_hi:[0,1,0]
	v_pk_fma_f32 v[26:27], v[8:9], v[76:77], v[26:27] op_sel:[0,1,0] op_sel_hi:[1,1,1]
	v_pk_fma_f32 v[12:13], v[62:63], v[22:23], v[36:37] op_sel:[1,0,0] op_sel_hi:[1,1,1] neg_lo:[0,1,0] neg_hi:[0,1,0]
	v_pk_fma_f32 v[26:27], v[10:11], v[78:79], v[26:27] op_sel:[0,0,0] op_sel_hi:[1,0,1]
	v_pk_fma_f32 v[14:15], v[64:65], v[22:23], v[38:39] op_sel:[0,0,0] op_sel_hi:[0,1,1] neg_lo:[0,1,0] neg_hi:[0,1,0]
	v_pk_fma_f32 v[26:27], v[12:13], v[78:79], v[26:27] op_sel:[0,1,0] op_sel_hi:[1,1,1]
	v_pk_fma_f32 v[16:17], v[64:65], v[22:23], v[40:41] op_sel:[1,0,0] op_sel_hi:[1,1,1] neg_lo:[0,1,0] neg_hi:[0,1,0]
	v_pk_fma_f32 v[26:27], v[14:15], v[80:81], v[26:27] op_sel:[0,0,0] op_sel_hi:[1,0,1]
	v_pk_fma_f32 v[18:19], v[66:67], v[22:23], v[42:43] op_sel:[0,0,0] op_sel_hi:[0,1,1] neg_lo:[0,1,0] neg_hi:[0,1,0]
	v_pk_fma_f32 v[26:27], v[16:17], v[80:81], v[26:27] op_sel:[0,1,0] op_sel_hi:[1,1,1]
	v_pk_fma_f32 v[20:21], v[66:67], v[22:23], v[44:45] op_sel:[1,0,0] op_sel_hi:[1,1,1] neg_lo:[0,1,0] neg_hi:[0,1,0]
	v_pk_fma_f32 v[26:27], v[18:19], v[82:83], v[26:27] op_sel:[0,0,0] op_sel_hi:[1,0,1]
	ds_write_b32 v49, v46 offset:640
	v_pk_fma_f32 v[26:27], v[20:21], v[82:83], v[26:27] op_sel:[0,1,0] op_sel_hi:[1,1,1]
	s_waitcnt lgkmcnt(1)
	v_pk_mul_f32 v[22:23], v[6:7], v[94:95] op_sel:[0,0] op_sel_hi:[1,0]
	v_pk_mul_f32 v[30:31], v[110:111], v[134:135] op_sel:[0,0] op_sel_hi:[0,1]
	ds_read_b128 v[52:55], v47 offset:2048
	v_pk_fma_f32 v[22:23], v[8:9], v[94:95], v[22:23] op_sel:[0,1,0] op_sel_hi:[1,1,1]
	v_pk_mul_f32 v[32:33], v[110:111], v[134:135] op_sel:[1,0] op_sel_hi:[1,1]
	ds_read_b128 v[56:59], v47 offset:2064
	v_pk_fma_f32 v[22:23], v[10:11], v[96:97], v[22:23] op_sel:[0,0,0] op_sel_hi:[1,0,1]
	v_pk_mul_f32 v[34:35], v[112:113], v[134:135] op_sel:[0,0] op_sel_hi:[0,1]
	ds_read_b128 v[68:71], v47 offset:10240
	v_pk_fma_f32 v[22:23], v[12:13], v[96:97], v[22:23] op_sel:[0,1,0] op_sel_hi:[1,1,1]
	v_pk_mul_f32 v[36:37], v[112:113], v[134:135] op_sel:[1,0] op_sel_hi:[1,1]
	ds_read_b128 v[72:75], v47 offset:10256
	v_pk_fma_f32 v[22:23], v[14:15], v[98:99], v[22:23] op_sel:[0,0,0] op_sel_hi:[1,0,1]
	v_pk_mul_f32 v[38:39], v[114:115], v[134:135] op_sel:[0,0] op_sel_hi:[0,1]
	ds_read_b64 v[92:93], v48 offset:2048
	v_pk_fma_f32 v[22:23], v[16:17], v[98:99], v[22:23] op_sel:[0,1,0] op_sel_hi:[1,1,1]
	v_pk_mul_f32 v[40:41], v[114:115], v[134:135] op_sel:[1,0] op_sel_hi:[1,1]
	ds_read_b128 v[84:87], v47 offset:18432
	v_pk_fma_f32 v[22:23], v[18:19], v[100:101], v[22:23] op_sel:[0,0,0] op_sel_hi:[1,0,1]
	v_pk_mul_f32 v[42:43], v[116:117], v[134:135] op_sel:[0,0] op_sel_hi:[0,1]
	ds_read_b128 v[88:91], v47 offset:18448
	v_pk_fma_f32 v[22:23], v[20:21], v[100:101], v[22:23] op_sel:[0,1,0] op_sel_hi:[1,1,1]
	v_pk_mul_f32 v[44:45], v[116:117], v[134:135] op_sel:[1,0] op_sel_hi:[1,1]
	ds_read_b128 v[60:63], v47 offset:6144
	v_pk_fma_f32 v[30:31], v[126:127], v[6:7], v[30:31] op_sel:[0,0,0] op_sel_hi:[0,1,1]
	v_pk_fma_f32 v[32:33], v[126:127], v[8:9], v[32:33] op_sel:[1,0,0] op_sel_hi:[1,1,1]
	ds_read_b128 v[64:67], v47 offset:6160
	v_pk_fma_f32 v[34:35], v[128:129], v[10:11], v[34:35] op_sel:[0,0,0] op_sel_hi:[0,1,1]
	v_pk_fma_f32 v[36:37], v[128:129], v[12:13], v[36:37] op_sel:[1,0,0] op_sel_hi:[1,1,1]
	ds_read_b128 v[76:79], v47 offset:14336
	v_add_f32_dpp v22, v22, v22 quad_perm:[1,0,3,2] row_mask:0xf bank_mask:0xf
	v_add_f32_dpp v23, v23, v23 quad_perm:[1,0,3,2] row_mask:0xf bank_mask:0xf
	ds_read_b128 v[80:83], v47 offset:14352
	v_add_f32_dpp v26, v26, v26 quad_perm:[1,0,3,2] row_mask:0xf bank_mask:0xf
	v_add_f32_dpp v27, v27, v27 quad_perm:[1,0,3,2] row_mask:0xf bank_mask:0xf
	v_pk_fma_f32 v[38:39], v[130:131], v[14:15], v[38:39] op_sel:[0,0,0] op_sel_hi:[0,1,1]
	v_pk_fma_f32 v[40:41], v[130:131], v[16:17], v[40:41] op_sel:[1,0,0] op_sel_hi:[1,1,1]
	v_add_f32_dpp v22, v22, v22 quad_perm:[2,3,0,1] row_mask:0xf bank_mask:0xf
	v_add_f32_dpp v23, v23, v23 quad_perm:[2,3,0,1] row_mask:0xf bank_mask:0xf
	v_add_f32_dpp v26, v26, v26 quad_perm:[2,3,0,1] row_mask:0xf bank_mask:0xf
	v_add_f32_dpp v27, v27, v27 quad_perm:[2,3,0,1] row_mask:0xf bank_mask:0xf
	v_pk_fma_f32 v[42:43], v[132:133], v[18:19], v[42:43] op_sel:[0,0,0] op_sel_hi:[0,1,1]
	v_pk_fma_f32 v[44:45], v[132:133], v[20:21], v[44:45] op_sel:[1,0,0] op_sel_hi:[1,1,1]
	v_add_f32_dpp v22, v22, v22 row_half_mirror row_mask:0xf bank_mask:0xf
	v_add_f32_dpp v23, v23, v23 row_half_mirror row_mask:0xf bank_mask:0xf
	v_add_f32_dpp v26, v26, v26 row_half_mirror row_mask:0xf bank_mask:0xf
	v_add_f32_dpp v27, v27, v27 row_half_mirror row_mask:0xf bank_mask:0xf
	v_pk_fma_f32 v[6:7], v[102:103], v[22:23], v[30:31] op_sel:[0,0,0] op_sel_hi:[0,1,1] neg_lo:[0,1,0] neg_hi:[0,1,0]
	v_cvt_pk_f16_f32 v46, v26, v27
	v_pk_fma_f32 v[8:9], v[102:103], v[22:23], v[32:33] op_sel:[1,0,0] op_sel_hi:[1,1,1] neg_lo:[0,1,0] neg_hi:[0,1,0]
	v_pk_mul_f32 v[26:27], v[6:7], v[118:119] op_sel:[0,0] op_sel_hi:[1,0]
	v_pk_fma_f32 v[10:11], v[104:105], v[22:23], v[34:35] op_sel:[0,0,0] op_sel_hi:[0,1,1] neg_lo:[0,1,0] neg_hi:[0,1,0]
	v_pk_fma_f32 v[26:27], v[8:9], v[118:119], v[26:27] op_sel:[0,1,0] op_sel_hi:[1,1,1]
	v_pk_fma_f32 v[12:13], v[104:105], v[22:23], v[36:37] op_sel:[1,0,0] op_sel_hi:[1,1,1] neg_lo:[0,1,0] neg_hi:[0,1,0]
	v_pk_fma_f32 v[26:27], v[10:11], v[120:121], v[26:27] op_sel:[0,0,0] op_sel_hi:[1,0,1]
	v_pk_fma_f32 v[14:15], v[106:107], v[22:23], v[38:39] op_sel:[0,0,0] op_sel_hi:[0,1,1] neg_lo:[0,1,0] neg_hi:[0,1,0]
	v_pk_fma_f32 v[26:27], v[12:13], v[120:121], v[26:27] op_sel:[0,1,0] op_sel_hi:[1,1,1]
	v_pk_fma_f32 v[16:17], v[106:107], v[22:23], v[40:41] op_sel:[1,0,0] op_sel_hi:[1,1,1] neg_lo:[0,1,0] neg_hi:[0,1,0]
	v_pk_fma_f32 v[26:27], v[14:15], v[122:123], v[26:27] op_sel:[0,0,0] op_sel_hi:[1,0,1]
	v_pk_fma_f32 v[18:19], v[108:109], v[22:23], v[42:43] op_sel:[0,0,0] op_sel_hi:[0,1,1] neg_lo:[0,1,0] neg_hi:[0,1,0]
	v_pk_fma_f32 v[26:27], v[16:17], v[122:123], v[26:27] op_sel:[0,1,0] op_sel_hi:[1,1,1]
	v_pk_fma_f32 v[20:21], v[108:109], v[22:23], v[44:45] op_sel:[1,0,0] op_sel_hi:[1,1,1] neg_lo:[0,1,0] neg_hi:[0,1,0]
	v_pk_fma_f32 v[26:27], v[18:19], v[124:125], v[26:27] op_sel:[0,0,0] op_sel_hi:[1,0,1]
	ds_write_b32 v49, v46 offset:768
	v_pk_fma_f32 v[26:27], v[20:21], v[124:125], v[26:27] op_sel:[0,1,0] op_sel_hi:[1,1,1]
	s_waitcnt lgkmcnt(1)
	v_pk_mul_f32 v[22:23], v[6:7], v[52:53] op_sel:[0,0] op_sel_hi:[1,0]
	v_pk_mul_f32 v[30:31], v[68:69], v[92:93] op_sel:[0,0] op_sel_hi:[0,1]
	ds_read_b128 v[94:97], v47 offset:2304
	v_pk_fma_f32 v[22:23], v[8:9], v[52:53], v[22:23] op_sel:[0,1,0] op_sel_hi:[1,1,1]
	v_pk_mul_f32 v[32:33], v[68:69], v[92:93] op_sel:[1,0] op_sel_hi:[1,1]
	ds_read_b128 v[98:101], v47 offset:2320
	v_pk_fma_f32 v[22:23], v[10:11], v[54:55], v[22:23] op_sel:[0,0,0] op_sel_hi:[1,0,1]
	v_pk_mul_f32 v[34:35], v[70:71], v[92:93] op_sel:[0,0] op_sel_hi:[0,1]
	ds_read_b128 v[110:113], v47 offset:10496
	v_pk_fma_f32 v[22:23], v[12:13], v[54:55], v[22:23] op_sel:[0,1,0] op_sel_hi:[1,1,1]
	v_pk_mul_f32 v[36:37], v[70:71], v[92:93] op_sel:[1,0] op_sel_hi:[1,1]
	ds_read_b128 v[114:117], v47 offset:10512
	v_pk_fma_f32 v[22:23], v[14:15], v[56:57], v[22:23] op_sel:[0,0,0] op_sel_hi:[1,0,1]
	v_pk_mul_f32 v[38:39], v[72:73], v[92:93] op_sel:[0,0] op_sel_hi:[0,1]
	ds_read_b64 v[134:135], v48 offset:2304
	v_pk_fma_f32 v[22:23], v[16:17], v[56:57], v[22:23] op_sel:[0,1,0] op_sel_hi:[1,1,1]
	v_pk_mul_f32 v[40:41], v[72:73], v[92:93] op_sel:[1,0] op_sel_hi:[1,1]
	ds_read_b128 v[126:129], v47 offset:18688
	v_pk_fma_f32 v[22:23], v[18:19], v[58:59], v[22:23] op_sel:[0,0,0] op_sel_hi:[1,0,1]
	v_pk_mul_f32 v[42:43], v[74:75], v[92:93] op_sel:[0,0] op_sel_hi:[0,1]
	ds_read_b128 v[130:133], v47 offset:18704
	v_pk_fma_f32 v[22:23], v[20:21], v[58:59], v[22:23] op_sel:[0,1,0] op_sel_hi:[1,1,1]
	v_pk_mul_f32 v[44:45], v[74:75], v[92:93] op_sel:[1,0] op_sel_hi:[1,1]
	ds_read_b128 v[102:105], v47 offset:6400
	v_pk_fma_f32 v[30:31], v[84:85], v[6:7], v[30:31] op_sel:[0,0,0] op_sel_hi:[0,1,1]
	v_pk_fma_f32 v[32:33], v[84:85], v[8:9], v[32:33] op_sel:[1,0,0] op_sel_hi:[1,1,1]
	ds_read_b128 v[106:109], v47 offset:6416
	v_pk_fma_f32 v[34:35], v[86:87], v[10:11], v[34:35] op_sel:[0,0,0] op_sel_hi:[0,1,1]
	v_pk_fma_f32 v[36:37], v[86:87], v[12:13], v[36:37] op_sel:[1,0,0] op_sel_hi:[1,1,1]
	ds_read_b128 v[118:121], v47 offset:14592
	v_add_f32_dpp v22, v22, v22 quad_perm:[1,0,3,2] row_mask:0xf bank_mask:0xf
	v_add_f32_dpp v23, v23, v23 quad_perm:[1,0,3,2] row_mask:0xf bank_mask:0xf
	ds_read_b128 v[122:125], v47 offset:14608
	v_add_f32_dpp v26, v26, v26 quad_perm:[1,0,3,2] row_mask:0xf bank_mask:0xf
	v_add_f32_dpp v27, v27, v27 quad_perm:[1,0,3,2] row_mask:0xf bank_mask:0xf
	v_pk_fma_f32 v[38:39], v[88:89], v[14:15], v[38:39] op_sel:[0,0,0] op_sel_hi:[0,1,1]
	v_pk_fma_f32 v[40:41], v[88:89], v[16:17], v[40:41] op_sel:[1,0,0] op_sel_hi:[1,1,1]
	v_add_f32_dpp v22, v22, v22 quad_perm:[2,3,0,1] row_mask:0xf bank_mask:0xf
	v_add_f32_dpp v23, v23, v23 quad_perm:[2,3,0,1] row_mask:0xf bank_mask:0xf
	v_add_f32_dpp v26, v26, v26 quad_perm:[2,3,0,1] row_mask:0xf bank_mask:0xf
	v_add_f32_dpp v27, v27, v27 quad_perm:[2,3,0,1] row_mask:0xf bank_mask:0xf
	v_pk_fma_f32 v[42:43], v[90:91], v[18:19], v[42:43] op_sel:[0,0,0] op_sel_hi:[0,1,1]
	v_pk_fma_f32 v[44:45], v[90:91], v[20:21], v[44:45] op_sel:[1,0,0] op_sel_hi:[1,1,1]
	v_add_f32_dpp v22, v22, v22 row_half_mirror row_mask:0xf bank_mask:0xf
	v_add_f32_dpp v23, v23, v23 row_half_mirror row_mask:0xf bank_mask:0xf
	v_add_f32_dpp v26, v26, v26 row_half_mirror row_mask:0xf bank_mask:0xf
	v_add_f32_dpp v27, v27, v27 row_half_mirror row_mask:0xf bank_mask:0xf
	v_pk_fma_f32 v[6:7], v[60:61], v[22:23], v[30:31] op_sel:[0,0,0] op_sel_hi:[0,1,1] neg_lo:[0,1,0] neg_hi:[0,1,0]
	v_cvt_pk_f16_f32 v46, v26, v27
	v_pk_fma_f32 v[8:9], v[60:61], v[22:23], v[32:33] op_sel:[1,0,0] op_sel_hi:[1,1,1] neg_lo:[0,1,0] neg_hi:[0,1,0]
	v_pk_mul_f32 v[26:27], v[6:7], v[76:77] op_sel:[0,0] op_sel_hi:[1,0]
	v_pk_fma_f32 v[10:11], v[62:63], v[22:23], v[34:35] op_sel:[0,0,0] op_sel_hi:[0,1,1] neg_lo:[0,1,0] neg_hi:[0,1,0]
	v_pk_fma_f32 v[26:27], v[8:9], v[76:77], v[26:27] op_sel:[0,1,0] op_sel_hi:[1,1,1]
	v_pk_fma_f32 v[12:13], v[62:63], v[22:23], v[36:37] op_sel:[1,0,0] op_sel_hi:[1,1,1] neg_lo:[0,1,0] neg_hi:[0,1,0]
	v_pk_fma_f32 v[26:27], v[10:11], v[78:79], v[26:27] op_sel:[0,0,0] op_sel_hi:[1,0,1]
	v_pk_fma_f32 v[14:15], v[64:65], v[22:23], v[38:39] op_sel:[0,0,0] op_sel_hi:[0,1,1] neg_lo:[0,1,0] neg_hi:[0,1,0]
	v_pk_fma_f32 v[26:27], v[12:13], v[78:79], v[26:27] op_sel:[0,1,0] op_sel_hi:[1,1,1]
	v_pk_fma_f32 v[16:17], v[64:65], v[22:23], v[40:41] op_sel:[1,0,0] op_sel_hi:[1,1,1] neg_lo:[0,1,0] neg_hi:[0,1,0]
	v_pk_fma_f32 v[26:27], v[14:15], v[80:81], v[26:27] op_sel:[0,0,0] op_sel_hi:[1,0,1]
	v_pk_fma_f32 v[18:19], v[66:67], v[22:23], v[42:43] op_sel:[0,0,0] op_sel_hi:[0,1,1] neg_lo:[0,1,0] neg_hi:[0,1,0]
	v_pk_fma_f32 v[26:27], v[16:17], v[80:81], v[26:27] op_sel:[0,1,0] op_sel_hi:[1,1,1]
	v_pk_fma_f32 v[20:21], v[66:67], v[22:23], v[44:45] op_sel:[1,0,0] op_sel_hi:[1,1,1] neg_lo:[0,1,0] neg_hi:[0,1,0]
	v_pk_fma_f32 v[26:27], v[18:19], v[82:83], v[26:27] op_sel:[0,0,0] op_sel_hi:[1,0,1]
	ds_write_b32 v49, v46 offset:896
	v_pk_fma_f32 v[26:27], v[20:21], v[82:83], v[26:27] op_sel:[0,1,0] op_sel_hi:[1,1,1]
	s_waitcnt lgkmcnt(1)
	v_pk_mul_f32 v[22:23], v[6:7], v[94:95] op_sel:[0,0] op_sel_hi:[1,0]
	v_pk_mul_f32 v[30:31], v[110:111], v[134:135] op_sel:[0,0] op_sel_hi:[0,1]
	ds_read_b128 v[52:55], v47 offset:2560
	v_pk_fma_f32 v[22:23], v[8:9], v[94:95], v[22:23] op_sel:[0,1,0] op_sel_hi:[1,1,1]
	v_pk_mul_f32 v[32:33], v[110:111], v[134:135] op_sel:[1,0] op_sel_hi:[1,1]
	ds_read_b128 v[56:59], v47 offset:2576
	v_pk_fma_f32 v[22:23], v[10:11], v[96:97], v[22:23] op_sel:[0,0,0] op_sel_hi:[1,0,1]
	v_pk_mul_f32 v[34:35], v[112:113], v[134:135] op_sel:[0,0] op_sel_hi:[0,1]
	ds_read_b128 v[68:71], v47 offset:10752
	v_pk_fma_f32 v[22:23], v[12:13], v[96:97], v[22:23] op_sel:[0,1,0] op_sel_hi:[1,1,1]
	v_pk_mul_f32 v[36:37], v[112:113], v[134:135] op_sel:[1,0] op_sel_hi:[1,1]
	ds_read_b128 v[72:75], v47 offset:10768
	v_pk_fma_f32 v[22:23], v[14:15], v[98:99], v[22:23] op_sel:[0,0,0] op_sel_hi:[1,0,1]
	v_pk_mul_f32 v[38:39], v[114:115], v[134:135] op_sel:[0,0] op_sel_hi:[0,1]
	ds_read_b64 v[92:93], v48 offset:2560
	v_pk_fma_f32 v[22:23], v[16:17], v[98:99], v[22:23] op_sel:[0,1,0] op_sel_hi:[1,1,1]
	v_pk_mul_f32 v[40:41], v[114:115], v[134:135] op_sel:[1,0] op_sel_hi:[1,1]
	ds_read_b128 v[84:87], v47 offset:18944
	v_pk_fma_f32 v[22:23], v[18:19], v[100:101], v[22:23] op_sel:[0,0,0] op_sel_hi:[1,0,1]
	v_pk_mul_f32 v[42:43], v[116:117], v[134:135] op_sel:[0,0] op_sel_hi:[0,1]
	ds_read_b128 v[88:91], v47 offset:18960
	v_pk_fma_f32 v[22:23], v[20:21], v[100:101], v[22:23] op_sel:[0,1,0] op_sel_hi:[1,1,1]
	v_pk_mul_f32 v[44:45], v[116:117], v[134:135] op_sel:[1,0] op_sel_hi:[1,1]
	ds_read_b128 v[60:63], v47 offset:6656
	v_pk_fma_f32 v[30:31], v[126:127], v[6:7], v[30:31] op_sel:[0,0,0] op_sel_hi:[0,1,1]
	v_pk_fma_f32 v[32:33], v[126:127], v[8:9], v[32:33] op_sel:[1,0,0] op_sel_hi:[1,1,1]
	ds_read_b128 v[64:67], v47 offset:6672
	v_pk_fma_f32 v[34:35], v[128:129], v[10:11], v[34:35] op_sel:[0,0,0] op_sel_hi:[0,1,1]
	v_pk_fma_f32 v[36:37], v[128:129], v[12:13], v[36:37] op_sel:[1,0,0] op_sel_hi:[1,1,1]
	ds_read_b128 v[76:79], v47 offset:14848
	v_add_f32_dpp v22, v22, v22 quad_perm:[1,0,3,2] row_mask:0xf bank_mask:0xf
	v_add_f32_dpp v23, v23, v23 quad_perm:[1,0,3,2] row_mask:0xf bank_mask:0xf
	ds_read_b128 v[80:83], v47 offset:14864
	v_add_f32_dpp v26, v26, v26 quad_perm:[1,0,3,2] row_mask:0xf bank_mask:0xf
	v_add_f32_dpp v27, v27, v27 quad_perm:[1,0,3,2] row_mask:0xf bank_mask:0xf
	v_pk_fma_f32 v[38:39], v[130:131], v[14:15], v[38:39] op_sel:[0,0,0] op_sel_hi:[0,1,1]
	v_pk_fma_f32 v[40:41], v[130:131], v[16:17], v[40:41] op_sel:[1,0,0] op_sel_hi:[1,1,1]
	v_add_f32_dpp v22, v22, v22 quad_perm:[2,3,0,1] row_mask:0xf bank_mask:0xf
	v_add_f32_dpp v23, v23, v23 quad_perm:[2,3,0,1] row_mask:0xf bank_mask:0xf
	v_add_f32_dpp v26, v26, v26 quad_perm:[2,3,0,1] row_mask:0xf bank_mask:0xf
	v_add_f32_dpp v27, v27, v27 quad_perm:[2,3,0,1] row_mask:0xf bank_mask:0xf
	v_pk_fma_f32 v[42:43], v[132:133], v[18:19], v[42:43] op_sel:[0,0,0] op_sel_hi:[0,1,1]
	v_pk_fma_f32 v[44:45], v[132:133], v[20:21], v[44:45] op_sel:[1,0,0] op_sel_hi:[1,1,1]
	v_add_f32_dpp v22, v22, v22 row_half_mirror row_mask:0xf bank_mask:0xf
	v_add_f32_dpp v23, v23, v23 row_half_mirror row_mask:0xf bank_mask:0xf
	v_add_f32_dpp v26, v26, v26 row_half_mirror row_mask:0xf bank_mask:0xf
	v_add_f32_dpp v27, v27, v27 row_half_mirror row_mask:0xf bank_mask:0xf
	v_pk_fma_f32 v[6:7], v[102:103], v[22:23], v[30:31] op_sel:[0,0,0] op_sel_hi:[0,1,1] neg_lo:[0,1,0] neg_hi:[0,1,0]
	v_cvt_pk_f16_f32 v46, v26, v27
	v_pk_fma_f32 v[8:9], v[102:103], v[22:23], v[32:33] op_sel:[1,0,0] op_sel_hi:[1,1,1] neg_lo:[0,1,0] neg_hi:[0,1,0]
	v_pk_mul_f32 v[26:27], v[6:7], v[118:119] op_sel:[0,0] op_sel_hi:[1,0]
	v_pk_fma_f32 v[10:11], v[104:105], v[22:23], v[34:35] op_sel:[0,0,0] op_sel_hi:[0,1,1] neg_lo:[0,1,0] neg_hi:[0,1,0]
	v_pk_fma_f32 v[26:27], v[8:9], v[118:119], v[26:27] op_sel:[0,1,0] op_sel_hi:[1,1,1]
	v_pk_fma_f32 v[12:13], v[104:105], v[22:23], v[36:37] op_sel:[1,0,0] op_sel_hi:[1,1,1] neg_lo:[0,1,0] neg_hi:[0,1,0]
	v_pk_fma_f32 v[26:27], v[10:11], v[120:121], v[26:27] op_sel:[0,0,0] op_sel_hi:[1,0,1]
	v_pk_fma_f32 v[14:15], v[106:107], v[22:23], v[38:39] op_sel:[0,0,0] op_sel_hi:[0,1,1] neg_lo:[0,1,0] neg_hi:[0,1,0]
	v_pk_fma_f32 v[26:27], v[12:13], v[120:121], v[26:27] op_sel:[0,1,0] op_sel_hi:[1,1,1]
	v_pk_fma_f32 v[16:17], v[106:107], v[22:23], v[40:41] op_sel:[1,0,0] op_sel_hi:[1,1,1] neg_lo:[0,1,0] neg_hi:[0,1,0]
	v_pk_fma_f32 v[26:27], v[14:15], v[122:123], v[26:27] op_sel:[0,0,0] op_sel_hi:[1,0,1]
	v_pk_fma_f32 v[18:19], v[108:109], v[22:23], v[42:43] op_sel:[0,0,0] op_sel_hi:[0,1,1] neg_lo:[0,1,0] neg_hi:[0,1,0]
	v_pk_fma_f32 v[26:27], v[16:17], v[122:123], v[26:27] op_sel:[0,1,0] op_sel_hi:[1,1,1]
	v_pk_fma_f32 v[20:21], v[108:109], v[22:23], v[44:45] op_sel:[1,0,0] op_sel_hi:[1,1,1] neg_lo:[0,1,0] neg_hi:[0,1,0]
	v_pk_fma_f32 v[26:27], v[18:19], v[124:125], v[26:27] op_sel:[0,0,0] op_sel_hi:[1,0,1]
	ds_write_b32 v49, v46 offset:1024
	v_pk_fma_f32 v[26:27], v[20:21], v[124:125], v[26:27] op_sel:[0,1,0] op_sel_hi:[1,1,1]
	s_waitcnt lgkmcnt(1)
	v_pk_mul_f32 v[22:23], v[6:7], v[52:53] op_sel:[0,0] op_sel_hi:[1,0]
	v_pk_mul_f32 v[30:31], v[68:69], v[92:93] op_sel:[0,0] op_sel_hi:[0,1]
	ds_read_b128 v[94:97], v47 offset:2816
	v_pk_fma_f32 v[22:23], v[8:9], v[52:53], v[22:23] op_sel:[0,1,0] op_sel_hi:[1,1,1]
	v_pk_mul_f32 v[32:33], v[68:69], v[92:93] op_sel:[1,0] op_sel_hi:[1,1]
	ds_read_b128 v[98:101], v47 offset:2832
	v_pk_fma_f32 v[22:23], v[10:11], v[54:55], v[22:23] op_sel:[0,0,0] op_sel_hi:[1,0,1]
	v_pk_mul_f32 v[34:35], v[70:71], v[92:93] op_sel:[0,0] op_sel_hi:[0,1]
	ds_read_b128 v[110:113], v47 offset:11008
	v_pk_fma_f32 v[22:23], v[12:13], v[54:55], v[22:23] op_sel:[0,1,0] op_sel_hi:[1,1,1]
	v_pk_mul_f32 v[36:37], v[70:71], v[92:93] op_sel:[1,0] op_sel_hi:[1,1]
	ds_read_b128 v[114:117], v47 offset:11024
	v_pk_fma_f32 v[22:23], v[14:15], v[56:57], v[22:23] op_sel:[0,0,0] op_sel_hi:[1,0,1]
	v_pk_mul_f32 v[38:39], v[72:73], v[92:93] op_sel:[0,0] op_sel_hi:[0,1]
	ds_read_b64 v[134:135], v48 offset:2816
	v_pk_fma_f32 v[22:23], v[16:17], v[56:57], v[22:23] op_sel:[0,1,0] op_sel_hi:[1,1,1]
	v_pk_mul_f32 v[40:41], v[72:73], v[92:93] op_sel:[1,0] op_sel_hi:[1,1]
	ds_read_b128 v[126:129], v47 offset:19200
	v_pk_fma_f32 v[22:23], v[18:19], v[58:59], v[22:23] op_sel:[0,0,0] op_sel_hi:[1,0,1]
	v_pk_mul_f32 v[42:43], v[74:75], v[92:93] op_sel:[0,0] op_sel_hi:[0,1]
	ds_read_b128 v[130:133], v47 offset:19216
	v_pk_fma_f32 v[22:23], v[20:21], v[58:59], v[22:23] op_sel:[0,1,0] op_sel_hi:[1,1,1]
	v_pk_mul_f32 v[44:45], v[74:75], v[92:93] op_sel:[1,0] op_sel_hi:[1,1]
	ds_read_b128 v[102:105], v47 offset:6912
	v_pk_fma_f32 v[30:31], v[84:85], v[6:7], v[30:31] op_sel:[0,0,0] op_sel_hi:[0,1,1]
	v_pk_fma_f32 v[32:33], v[84:85], v[8:9], v[32:33] op_sel:[1,0,0] op_sel_hi:[1,1,1]
	ds_read_b128 v[106:109], v47 offset:6928
	v_pk_fma_f32 v[34:35], v[86:87], v[10:11], v[34:35] op_sel:[0,0,0] op_sel_hi:[0,1,1]
	v_pk_fma_f32 v[36:37], v[86:87], v[12:13], v[36:37] op_sel:[1,0,0] op_sel_hi:[1,1,1]
	ds_read_b128 v[118:121], v47 offset:15104
	v_add_f32_dpp v22, v22, v22 quad_perm:[1,0,3,2] row_mask:0xf bank_mask:0xf
	v_add_f32_dpp v23, v23, v23 quad_perm:[1,0,3,2] row_mask:0xf bank_mask:0xf
	ds_read_b128 v[122:125], v47 offset:15120
	v_add_f32_dpp v26, v26, v26 quad_perm:[1,0,3,2] row_mask:0xf bank_mask:0xf
	v_add_f32_dpp v27, v27, v27 quad_perm:[1,0,3,2] row_mask:0xf bank_mask:0xf
	v_pk_fma_f32 v[38:39], v[88:89], v[14:15], v[38:39] op_sel:[0,0,0] op_sel_hi:[0,1,1]
	v_pk_fma_f32 v[40:41], v[88:89], v[16:17], v[40:41] op_sel:[1,0,0] op_sel_hi:[1,1,1]
	v_add_f32_dpp v22, v22, v22 quad_perm:[2,3,0,1] row_mask:0xf bank_mask:0xf
	v_add_f32_dpp v23, v23, v23 quad_perm:[2,3,0,1] row_mask:0xf bank_mask:0xf
	v_add_f32_dpp v26, v26, v26 quad_perm:[2,3,0,1] row_mask:0xf bank_mask:0xf
	v_add_f32_dpp v27, v27, v27 quad_perm:[2,3,0,1] row_mask:0xf bank_mask:0xf
	v_pk_fma_f32 v[42:43], v[90:91], v[18:19], v[42:43] op_sel:[0,0,0] op_sel_hi:[0,1,1]
	v_pk_fma_f32 v[44:45], v[90:91], v[20:21], v[44:45] op_sel:[1,0,0] op_sel_hi:[1,1,1]
	v_add_f32_dpp v22, v22, v22 row_half_mirror row_mask:0xf bank_mask:0xf
	v_add_f32_dpp v23, v23, v23 row_half_mirror row_mask:0xf bank_mask:0xf
	v_add_f32_dpp v26, v26, v26 row_half_mirror row_mask:0xf bank_mask:0xf
	v_add_f32_dpp v27, v27, v27 row_half_mirror row_mask:0xf bank_mask:0xf
	v_pk_fma_f32 v[6:7], v[60:61], v[22:23], v[30:31] op_sel:[0,0,0] op_sel_hi:[0,1,1] neg_lo:[0,1,0] neg_hi:[0,1,0]
	v_cvt_pk_f16_f32 v46, v26, v27
	v_pk_fma_f32 v[8:9], v[60:61], v[22:23], v[32:33] op_sel:[1,0,0] op_sel_hi:[1,1,1] neg_lo:[0,1,0] neg_hi:[0,1,0]
	v_pk_mul_f32 v[26:27], v[6:7], v[76:77] op_sel:[0,0] op_sel_hi:[1,0]
	v_pk_fma_f32 v[10:11], v[62:63], v[22:23], v[34:35] op_sel:[0,0,0] op_sel_hi:[0,1,1] neg_lo:[0,1,0] neg_hi:[0,1,0]
	v_pk_fma_f32 v[26:27], v[8:9], v[76:77], v[26:27] op_sel:[0,1,0] op_sel_hi:[1,1,1]
	v_pk_fma_f32 v[12:13], v[62:63], v[22:23], v[36:37] op_sel:[1,0,0] op_sel_hi:[1,1,1] neg_lo:[0,1,0] neg_hi:[0,1,0]
	v_pk_fma_f32 v[26:27], v[10:11], v[78:79], v[26:27] op_sel:[0,0,0] op_sel_hi:[1,0,1]
	v_pk_fma_f32 v[14:15], v[64:65], v[22:23], v[38:39] op_sel:[0,0,0] op_sel_hi:[0,1,1] neg_lo:[0,1,0] neg_hi:[0,1,0]
	v_pk_fma_f32 v[26:27], v[12:13], v[78:79], v[26:27] op_sel:[0,1,0] op_sel_hi:[1,1,1]
	v_pk_fma_f32 v[16:17], v[64:65], v[22:23], v[40:41] op_sel:[1,0,0] op_sel_hi:[1,1,1] neg_lo:[0,1,0] neg_hi:[0,1,0]
	v_pk_fma_f32 v[26:27], v[14:15], v[80:81], v[26:27] op_sel:[0,0,0] op_sel_hi:[1,0,1]
	v_pk_fma_f32 v[18:19], v[66:67], v[22:23], v[42:43] op_sel:[0,0,0] op_sel_hi:[0,1,1] neg_lo:[0,1,0] neg_hi:[0,1,0]
	v_pk_fma_f32 v[26:27], v[16:17], v[80:81], v[26:27] op_sel:[0,1,0] op_sel_hi:[1,1,1]
	v_pk_fma_f32 v[20:21], v[66:67], v[22:23], v[44:45] op_sel:[1,0,0] op_sel_hi:[1,1,1] neg_lo:[0,1,0] neg_hi:[0,1,0]
	v_pk_fma_f32 v[26:27], v[18:19], v[82:83], v[26:27] op_sel:[0,0,0] op_sel_hi:[1,0,1]
	ds_write_b32 v49, v46 offset:1152
	v_pk_fma_f32 v[26:27], v[20:21], v[82:83], v[26:27] op_sel:[0,1,0] op_sel_hi:[1,1,1]
	s_waitcnt lgkmcnt(1)
	v_pk_mul_f32 v[22:23], v[6:7], v[94:95] op_sel:[0,0] op_sel_hi:[1,0]
	v_pk_mul_f32 v[30:31], v[110:111], v[134:135] op_sel:[0,0] op_sel_hi:[0,1]
	ds_read_b128 v[52:55], v47 offset:3072
	v_pk_fma_f32 v[22:23], v[8:9], v[94:95], v[22:23] op_sel:[0,1,0] op_sel_hi:[1,1,1]
	v_pk_mul_f32 v[32:33], v[110:111], v[134:135] op_sel:[1,0] op_sel_hi:[1,1]
	ds_read_b128 v[56:59], v47 offset:3088
	v_pk_fma_f32 v[22:23], v[10:11], v[96:97], v[22:23] op_sel:[0,0,0] op_sel_hi:[1,0,1]
	v_pk_mul_f32 v[34:35], v[112:113], v[134:135] op_sel:[0,0] op_sel_hi:[0,1]
	ds_read_b128 v[68:71], v47 offset:11264
	v_pk_fma_f32 v[22:23], v[12:13], v[96:97], v[22:23] op_sel:[0,1,0] op_sel_hi:[1,1,1]
	v_pk_mul_f32 v[36:37], v[112:113], v[134:135] op_sel:[1,0] op_sel_hi:[1,1]
	ds_read_b128 v[72:75], v47 offset:11280
	v_pk_fma_f32 v[22:23], v[14:15], v[98:99], v[22:23] op_sel:[0,0,0] op_sel_hi:[1,0,1]
	v_pk_mul_f32 v[38:39], v[114:115], v[134:135] op_sel:[0,0] op_sel_hi:[0,1]
	ds_read_b64 v[92:93], v48 offset:3072
	v_pk_fma_f32 v[22:23], v[16:17], v[98:99], v[22:23] op_sel:[0,1,0] op_sel_hi:[1,1,1]
	v_pk_mul_f32 v[40:41], v[114:115], v[134:135] op_sel:[1,0] op_sel_hi:[1,1]
	ds_read_b128 v[84:87], v47 offset:19456
	v_pk_fma_f32 v[22:23], v[18:19], v[100:101], v[22:23] op_sel:[0,0,0] op_sel_hi:[1,0,1]
	v_pk_mul_f32 v[42:43], v[116:117], v[134:135] op_sel:[0,0] op_sel_hi:[0,1]
	ds_read_b128 v[88:91], v47 offset:19472
	v_pk_fma_f32 v[22:23], v[20:21], v[100:101], v[22:23] op_sel:[0,1,0] op_sel_hi:[1,1,1]
	v_pk_mul_f32 v[44:45], v[116:117], v[134:135] op_sel:[1,0] op_sel_hi:[1,1]
	ds_read_b128 v[60:63], v47 offset:7168
	v_pk_fma_f32 v[30:31], v[126:127], v[6:7], v[30:31] op_sel:[0,0,0] op_sel_hi:[0,1,1]
	v_pk_fma_f32 v[32:33], v[126:127], v[8:9], v[32:33] op_sel:[1,0,0] op_sel_hi:[1,1,1]
	ds_read_b128 v[64:67], v47 offset:7184
	v_pk_fma_f32 v[34:35], v[128:129], v[10:11], v[34:35] op_sel:[0,0,0] op_sel_hi:[0,1,1]
	v_pk_fma_f32 v[36:37], v[128:129], v[12:13], v[36:37] op_sel:[1,0,0] op_sel_hi:[1,1,1]
	ds_read_b128 v[76:79], v47 offset:15360
	v_add_f32_dpp v22, v22, v22 quad_perm:[1,0,3,2] row_mask:0xf bank_mask:0xf
	v_add_f32_dpp v23, v23, v23 quad_perm:[1,0,3,2] row_mask:0xf bank_mask:0xf
	ds_read_b128 v[80:83], v47 offset:15376
	v_add_f32_dpp v26, v26, v26 quad_perm:[1,0,3,2] row_mask:0xf bank_mask:0xf
	v_add_f32_dpp v27, v27, v27 quad_perm:[1,0,3,2] row_mask:0xf bank_mask:0xf
	v_pk_fma_f32 v[38:39], v[130:131], v[14:15], v[38:39] op_sel:[0,0,0] op_sel_hi:[0,1,1]
	v_pk_fma_f32 v[40:41], v[130:131], v[16:17], v[40:41] op_sel:[1,0,0] op_sel_hi:[1,1,1]
	v_add_f32_dpp v22, v22, v22 quad_perm:[2,3,0,1] row_mask:0xf bank_mask:0xf
	v_add_f32_dpp v23, v23, v23 quad_perm:[2,3,0,1] row_mask:0xf bank_mask:0xf
	v_add_f32_dpp v26, v26, v26 quad_perm:[2,3,0,1] row_mask:0xf bank_mask:0xf
	v_add_f32_dpp v27, v27, v27 quad_perm:[2,3,0,1] row_mask:0xf bank_mask:0xf
	v_pk_fma_f32 v[42:43], v[132:133], v[18:19], v[42:43] op_sel:[0,0,0] op_sel_hi:[0,1,1]
	v_pk_fma_f32 v[44:45], v[132:133], v[20:21], v[44:45] op_sel:[1,0,0] op_sel_hi:[1,1,1]
	v_add_f32_dpp v22, v22, v22 row_half_mirror row_mask:0xf bank_mask:0xf
	v_add_f32_dpp v23, v23, v23 row_half_mirror row_mask:0xf bank_mask:0xf
	v_add_f32_dpp v26, v26, v26 row_half_mirror row_mask:0xf bank_mask:0xf
	v_add_f32_dpp v27, v27, v27 row_half_mirror row_mask:0xf bank_mask:0xf
	v_pk_fma_f32 v[6:7], v[102:103], v[22:23], v[30:31] op_sel:[0,0,0] op_sel_hi:[0,1,1] neg_lo:[0,1,0] neg_hi:[0,1,0]
	v_cvt_pk_f16_f32 v46, v26, v27
	v_pk_fma_f32 v[8:9], v[102:103], v[22:23], v[32:33] op_sel:[1,0,0] op_sel_hi:[1,1,1] neg_lo:[0,1,0] neg_hi:[0,1,0]
	v_pk_mul_f32 v[26:27], v[6:7], v[118:119] op_sel:[0,0] op_sel_hi:[1,0]
	v_pk_fma_f32 v[10:11], v[104:105], v[22:23], v[34:35] op_sel:[0,0,0] op_sel_hi:[0,1,1] neg_lo:[0,1,0] neg_hi:[0,1,0]
	v_pk_fma_f32 v[26:27], v[8:9], v[118:119], v[26:27] op_sel:[0,1,0] op_sel_hi:[1,1,1]
	v_pk_fma_f32 v[12:13], v[104:105], v[22:23], v[36:37] op_sel:[1,0,0] op_sel_hi:[1,1,1] neg_lo:[0,1,0] neg_hi:[0,1,0]
	v_pk_fma_f32 v[26:27], v[10:11], v[120:121], v[26:27] op_sel:[0,0,0] op_sel_hi:[1,0,1]
	v_pk_fma_f32 v[14:15], v[106:107], v[22:23], v[38:39] op_sel:[0,0,0] op_sel_hi:[0,1,1] neg_lo:[0,1,0] neg_hi:[0,1,0]
	v_pk_fma_f32 v[26:27], v[12:13], v[120:121], v[26:27] op_sel:[0,1,0] op_sel_hi:[1,1,1]
	v_pk_fma_f32 v[16:17], v[106:107], v[22:23], v[40:41] op_sel:[1,0,0] op_sel_hi:[1,1,1] neg_lo:[0,1,0] neg_hi:[0,1,0]
	v_pk_fma_f32 v[26:27], v[14:15], v[122:123], v[26:27] op_sel:[0,0,0] op_sel_hi:[1,0,1]
	v_pk_fma_f32 v[18:19], v[108:109], v[22:23], v[42:43] op_sel:[0,0,0] op_sel_hi:[0,1,1] neg_lo:[0,1,0] neg_hi:[0,1,0]
	v_pk_fma_f32 v[26:27], v[16:17], v[122:123], v[26:27] op_sel:[0,1,0] op_sel_hi:[1,1,1]
	v_pk_fma_f32 v[20:21], v[108:109], v[22:23], v[44:45] op_sel:[1,0,0] op_sel_hi:[1,1,1] neg_lo:[0,1,0] neg_hi:[0,1,0]
	v_pk_fma_f32 v[26:27], v[18:19], v[124:125], v[26:27] op_sel:[0,0,0] op_sel_hi:[1,0,1]
	ds_write_b32 v49, v46 offset:1280
	v_pk_fma_f32 v[26:27], v[20:21], v[124:125], v[26:27] op_sel:[0,1,0] op_sel_hi:[1,1,1]
	s_waitcnt lgkmcnt(1)
	v_pk_mul_f32 v[22:23], v[6:7], v[52:53] op_sel:[0,0] op_sel_hi:[1,0]
	v_pk_mul_f32 v[30:31], v[68:69], v[92:93] op_sel:[0,0] op_sel_hi:[0,1]
	ds_read_b128 v[94:97], v47 offset:3328
	v_pk_fma_f32 v[22:23], v[8:9], v[52:53], v[22:23] op_sel:[0,1,0] op_sel_hi:[1,1,1]
	v_pk_mul_f32 v[32:33], v[68:69], v[92:93] op_sel:[1,0] op_sel_hi:[1,1]
	ds_read_b128 v[98:101], v47 offset:3344
	v_pk_fma_f32 v[22:23], v[10:11], v[54:55], v[22:23] op_sel:[0,0,0] op_sel_hi:[1,0,1]
	v_pk_mul_f32 v[34:35], v[70:71], v[92:93] op_sel:[0,0] op_sel_hi:[0,1]
	ds_read_b128 v[110:113], v47 offset:11520
	v_pk_fma_f32 v[22:23], v[12:13], v[54:55], v[22:23] op_sel:[0,1,0] op_sel_hi:[1,1,1]
	v_pk_mul_f32 v[36:37], v[70:71], v[92:93] op_sel:[1,0] op_sel_hi:[1,1]
	ds_read_b128 v[114:117], v47 offset:11536
	v_pk_fma_f32 v[22:23], v[14:15], v[56:57], v[22:23] op_sel:[0,0,0] op_sel_hi:[1,0,1]
	v_pk_mul_f32 v[38:39], v[72:73], v[92:93] op_sel:[0,0] op_sel_hi:[0,1]
	ds_read_b64 v[134:135], v48 offset:3328
	v_pk_fma_f32 v[22:23], v[16:17], v[56:57], v[22:23] op_sel:[0,1,0] op_sel_hi:[1,1,1]
	v_pk_mul_f32 v[40:41], v[72:73], v[92:93] op_sel:[1,0] op_sel_hi:[1,1]
	ds_read_b128 v[126:129], v47 offset:19712
	v_pk_fma_f32 v[22:23], v[18:19], v[58:59], v[22:23] op_sel:[0,0,0] op_sel_hi:[1,0,1]
	v_pk_mul_f32 v[42:43], v[74:75], v[92:93] op_sel:[0,0] op_sel_hi:[0,1]
	ds_read_b128 v[130:133], v47 offset:19728
	v_pk_fma_f32 v[22:23], v[20:21], v[58:59], v[22:23] op_sel:[0,1,0] op_sel_hi:[1,1,1]
	v_pk_mul_f32 v[44:45], v[74:75], v[92:93] op_sel:[1,0] op_sel_hi:[1,1]
	ds_read_b128 v[102:105], v47 offset:7424
	v_pk_fma_f32 v[30:31], v[84:85], v[6:7], v[30:31] op_sel:[0,0,0] op_sel_hi:[0,1,1]
	v_pk_fma_f32 v[32:33], v[84:85], v[8:9], v[32:33] op_sel:[1,0,0] op_sel_hi:[1,1,1]
	ds_read_b128 v[106:109], v47 offset:7440
	v_pk_fma_f32 v[34:35], v[86:87], v[10:11], v[34:35] op_sel:[0,0,0] op_sel_hi:[0,1,1]
	v_pk_fma_f32 v[36:37], v[86:87], v[12:13], v[36:37] op_sel:[1,0,0] op_sel_hi:[1,1,1]
	ds_read_b128 v[118:121], v47 offset:15616
	v_add_f32_dpp v22, v22, v22 quad_perm:[1,0,3,2] row_mask:0xf bank_mask:0xf
	v_add_f32_dpp v23, v23, v23 quad_perm:[1,0,3,2] row_mask:0xf bank_mask:0xf
	ds_read_b128 v[122:125], v47 offset:15632
	v_add_f32_dpp v26, v26, v26 quad_perm:[1,0,3,2] row_mask:0xf bank_mask:0xf
	v_add_f32_dpp v27, v27, v27 quad_perm:[1,0,3,2] row_mask:0xf bank_mask:0xf
	v_pk_fma_f32 v[38:39], v[88:89], v[14:15], v[38:39] op_sel:[0,0,0] op_sel_hi:[0,1,1]
	v_pk_fma_f32 v[40:41], v[88:89], v[16:17], v[40:41] op_sel:[1,0,0] op_sel_hi:[1,1,1]
	v_add_f32_dpp v22, v22, v22 quad_perm:[2,3,0,1] row_mask:0xf bank_mask:0xf
	v_add_f32_dpp v23, v23, v23 quad_perm:[2,3,0,1] row_mask:0xf bank_mask:0xf
	v_add_f32_dpp v26, v26, v26 quad_perm:[2,3,0,1] row_mask:0xf bank_mask:0xf
	v_add_f32_dpp v27, v27, v27 quad_perm:[2,3,0,1] row_mask:0xf bank_mask:0xf
	v_pk_fma_f32 v[42:43], v[90:91], v[18:19], v[42:43] op_sel:[0,0,0] op_sel_hi:[0,1,1]
	v_pk_fma_f32 v[44:45], v[90:91], v[20:21], v[44:45] op_sel:[1,0,0] op_sel_hi:[1,1,1]
	v_add_f32_dpp v22, v22, v22 row_half_mirror row_mask:0xf bank_mask:0xf
	v_add_f32_dpp v23, v23, v23 row_half_mirror row_mask:0xf bank_mask:0xf
	v_add_f32_dpp v26, v26, v26 row_half_mirror row_mask:0xf bank_mask:0xf
	v_add_f32_dpp v27, v27, v27 row_half_mirror row_mask:0xf bank_mask:0xf
	v_pk_fma_f32 v[6:7], v[60:61], v[22:23], v[30:31] op_sel:[0,0,0] op_sel_hi:[0,1,1] neg_lo:[0,1,0] neg_hi:[0,1,0]
	v_cvt_pk_f16_f32 v46, v26, v27
	v_pk_fma_f32 v[8:9], v[60:61], v[22:23], v[32:33] op_sel:[1,0,0] op_sel_hi:[1,1,1] neg_lo:[0,1,0] neg_hi:[0,1,0]
	v_pk_mul_f32 v[26:27], v[6:7], v[76:77] op_sel:[0,0] op_sel_hi:[1,0]
	v_pk_fma_f32 v[10:11], v[62:63], v[22:23], v[34:35] op_sel:[0,0,0] op_sel_hi:[0,1,1] neg_lo:[0,1,0] neg_hi:[0,1,0]
	v_pk_fma_f32 v[26:27], v[8:9], v[76:77], v[26:27] op_sel:[0,1,0] op_sel_hi:[1,1,1]
	v_pk_fma_f32 v[12:13], v[62:63], v[22:23], v[36:37] op_sel:[1,0,0] op_sel_hi:[1,1,1] neg_lo:[0,1,0] neg_hi:[0,1,0]
	v_pk_fma_f32 v[26:27], v[10:11], v[78:79], v[26:27] op_sel:[0,0,0] op_sel_hi:[1,0,1]
	v_pk_fma_f32 v[14:15], v[64:65], v[22:23], v[38:39] op_sel:[0,0,0] op_sel_hi:[0,1,1] neg_lo:[0,1,0] neg_hi:[0,1,0]
	v_pk_fma_f32 v[26:27], v[12:13], v[78:79], v[26:27] op_sel:[0,1,0] op_sel_hi:[1,1,1]
	v_pk_fma_f32 v[16:17], v[64:65], v[22:23], v[40:41] op_sel:[1,0,0] op_sel_hi:[1,1,1] neg_lo:[0,1,0] neg_hi:[0,1,0]
	v_pk_fma_f32 v[26:27], v[14:15], v[80:81], v[26:27] op_sel:[0,0,0] op_sel_hi:[1,0,1]
	v_pk_fma_f32 v[18:19], v[66:67], v[22:23], v[42:43] op_sel:[0,0,0] op_sel_hi:[0,1,1] neg_lo:[0,1,0] neg_hi:[0,1,0]
	v_pk_fma_f32 v[26:27], v[16:17], v[80:81], v[26:27] op_sel:[0,1,0] op_sel_hi:[1,1,1]
	v_pk_fma_f32 v[20:21], v[66:67], v[22:23], v[44:45] op_sel:[1,0,0] op_sel_hi:[1,1,1] neg_lo:[0,1,0] neg_hi:[0,1,0]
	v_pk_fma_f32 v[26:27], v[18:19], v[82:83], v[26:27] op_sel:[0,0,0] op_sel_hi:[1,0,1]
	ds_write_b32 v49, v46 offset:1408
	v_pk_fma_f32 v[26:27], v[20:21], v[82:83], v[26:27] op_sel:[0,1,0] op_sel_hi:[1,1,1]
	s_waitcnt lgkmcnt(1)
	v_pk_mul_f32 v[22:23], v[6:7], v[94:95] op_sel:[0,0] op_sel_hi:[1,0]
	v_pk_mul_f32 v[30:31], v[110:111], v[134:135] op_sel:[0,0] op_sel_hi:[0,1]
	ds_read_b128 v[52:55], v47 offset:3584
	v_pk_fma_f32 v[22:23], v[8:9], v[94:95], v[22:23] op_sel:[0,1,0] op_sel_hi:[1,1,1]
	v_pk_mul_f32 v[32:33], v[110:111], v[134:135] op_sel:[1,0] op_sel_hi:[1,1]
	ds_read_b128 v[56:59], v47 offset:3600
	v_pk_fma_f32 v[22:23], v[10:11], v[96:97], v[22:23] op_sel:[0,0,0] op_sel_hi:[1,0,1]
	v_pk_mul_f32 v[34:35], v[112:113], v[134:135] op_sel:[0,0] op_sel_hi:[0,1]
	ds_read_b128 v[68:71], v47 offset:11776
	v_pk_fma_f32 v[22:23], v[12:13], v[96:97], v[22:23] op_sel:[0,1,0] op_sel_hi:[1,1,1]
	v_pk_mul_f32 v[36:37], v[112:113], v[134:135] op_sel:[1,0] op_sel_hi:[1,1]
	ds_read_b128 v[72:75], v47 offset:11792
	v_pk_fma_f32 v[22:23], v[14:15], v[98:99], v[22:23] op_sel:[0,0,0] op_sel_hi:[1,0,1]
	v_pk_mul_f32 v[38:39], v[114:115], v[134:135] op_sel:[0,0] op_sel_hi:[0,1]
	ds_read_b64 v[92:93], v48 offset:3584
	v_pk_fma_f32 v[22:23], v[16:17], v[98:99], v[22:23] op_sel:[0,1,0] op_sel_hi:[1,1,1]
	v_pk_mul_f32 v[40:41], v[114:115], v[134:135] op_sel:[1,0] op_sel_hi:[1,1]
	ds_read_b128 v[84:87], v47 offset:19968
	v_pk_fma_f32 v[22:23], v[18:19], v[100:101], v[22:23] op_sel:[0,0,0] op_sel_hi:[1,0,1]
	v_pk_mul_f32 v[42:43], v[116:117], v[134:135] op_sel:[0,0] op_sel_hi:[0,1]
	ds_read_b128 v[88:91], v47 offset:19984
	v_pk_fma_f32 v[22:23], v[20:21], v[100:101], v[22:23] op_sel:[0,1,0] op_sel_hi:[1,1,1]
	v_pk_mul_f32 v[44:45], v[116:117], v[134:135] op_sel:[1,0] op_sel_hi:[1,1]
	ds_read_b128 v[60:63], v47 offset:7680
	v_pk_fma_f32 v[30:31], v[126:127], v[6:7], v[30:31] op_sel:[0,0,0] op_sel_hi:[0,1,1]
	v_pk_fma_f32 v[32:33], v[126:127], v[8:9], v[32:33] op_sel:[1,0,0] op_sel_hi:[1,1,1]
	ds_read_b128 v[64:67], v47 offset:7696
	v_pk_fma_f32 v[34:35], v[128:129], v[10:11], v[34:35] op_sel:[0,0,0] op_sel_hi:[0,1,1]
	v_pk_fma_f32 v[36:37], v[128:129], v[12:13], v[36:37] op_sel:[1,0,0] op_sel_hi:[1,1,1]
	ds_read_b128 v[76:79], v47 offset:15872
	v_add_f32_dpp v22, v22, v22 quad_perm:[1,0,3,2] row_mask:0xf bank_mask:0xf
	v_add_f32_dpp v23, v23, v23 quad_perm:[1,0,3,2] row_mask:0xf bank_mask:0xf
	ds_read_b128 v[80:83], v47 offset:15888
	v_add_f32_dpp v26, v26, v26 quad_perm:[1,0,3,2] row_mask:0xf bank_mask:0xf
	v_add_f32_dpp v27, v27, v27 quad_perm:[1,0,3,2] row_mask:0xf bank_mask:0xf
	v_pk_fma_f32 v[38:39], v[130:131], v[14:15], v[38:39] op_sel:[0,0,0] op_sel_hi:[0,1,1]
	v_pk_fma_f32 v[40:41], v[130:131], v[16:17], v[40:41] op_sel:[1,0,0] op_sel_hi:[1,1,1]
	v_add_f32_dpp v22, v22, v22 quad_perm:[2,3,0,1] row_mask:0xf bank_mask:0xf
	v_add_f32_dpp v23, v23, v23 quad_perm:[2,3,0,1] row_mask:0xf bank_mask:0xf
	v_add_f32_dpp v26, v26, v26 quad_perm:[2,3,0,1] row_mask:0xf bank_mask:0xf
	v_add_f32_dpp v27, v27, v27 quad_perm:[2,3,0,1] row_mask:0xf bank_mask:0xf
	v_pk_fma_f32 v[42:43], v[132:133], v[18:19], v[42:43] op_sel:[0,0,0] op_sel_hi:[0,1,1]
	v_pk_fma_f32 v[44:45], v[132:133], v[20:21], v[44:45] op_sel:[1,0,0] op_sel_hi:[1,1,1]
	v_add_f32_dpp v22, v22, v22 row_half_mirror row_mask:0xf bank_mask:0xf
	v_add_f32_dpp v23, v23, v23 row_half_mirror row_mask:0xf bank_mask:0xf
	v_add_f32_dpp v26, v26, v26 row_half_mirror row_mask:0xf bank_mask:0xf
	v_add_f32_dpp v27, v27, v27 row_half_mirror row_mask:0xf bank_mask:0xf
	v_pk_fma_f32 v[6:7], v[102:103], v[22:23], v[30:31] op_sel:[0,0,0] op_sel_hi:[0,1,1] neg_lo:[0,1,0] neg_hi:[0,1,0]
	v_cvt_pk_f16_f32 v46, v26, v27
	v_pk_fma_f32 v[8:9], v[102:103], v[22:23], v[32:33] op_sel:[1,0,0] op_sel_hi:[1,1,1] neg_lo:[0,1,0] neg_hi:[0,1,0]
	v_pk_mul_f32 v[26:27], v[6:7], v[118:119] op_sel:[0,0] op_sel_hi:[1,0]
	v_pk_fma_f32 v[10:11], v[104:105], v[22:23], v[34:35] op_sel:[0,0,0] op_sel_hi:[0,1,1] neg_lo:[0,1,0] neg_hi:[0,1,0]
	v_pk_fma_f32 v[26:27], v[8:9], v[118:119], v[26:27] op_sel:[0,1,0] op_sel_hi:[1,1,1]
	v_pk_fma_f32 v[12:13], v[104:105], v[22:23], v[36:37] op_sel:[1,0,0] op_sel_hi:[1,1,1] neg_lo:[0,1,0] neg_hi:[0,1,0]
	v_pk_fma_f32 v[26:27], v[10:11], v[120:121], v[26:27] op_sel:[0,0,0] op_sel_hi:[1,0,1]
	v_pk_fma_f32 v[14:15], v[106:107], v[22:23], v[38:39] op_sel:[0,0,0] op_sel_hi:[0,1,1] neg_lo:[0,1,0] neg_hi:[0,1,0]
	v_pk_fma_f32 v[26:27], v[12:13], v[120:121], v[26:27] op_sel:[0,1,0] op_sel_hi:[1,1,1]
	v_pk_fma_f32 v[16:17], v[106:107], v[22:23], v[40:41] op_sel:[1,0,0] op_sel_hi:[1,1,1] neg_lo:[0,1,0] neg_hi:[0,1,0]
	v_pk_fma_f32 v[26:27], v[14:15], v[122:123], v[26:27] op_sel:[0,0,0] op_sel_hi:[1,0,1]
	v_pk_fma_f32 v[18:19], v[108:109], v[22:23], v[42:43] op_sel:[0,0,0] op_sel_hi:[0,1,1] neg_lo:[0,1,0] neg_hi:[0,1,0]
	v_pk_fma_f32 v[26:27], v[16:17], v[122:123], v[26:27] op_sel:[0,1,0] op_sel_hi:[1,1,1]
	v_pk_fma_f32 v[20:21], v[108:109], v[22:23], v[44:45] op_sel:[1,0,0] op_sel_hi:[1,1,1] neg_lo:[0,1,0] neg_hi:[0,1,0]
	v_pk_fma_f32 v[26:27], v[18:19], v[124:125], v[26:27] op_sel:[0,0,0] op_sel_hi:[1,0,1]
	ds_write_b32 v49, v46 offset:1536
	v_pk_fma_f32 v[26:27], v[20:21], v[124:125], v[26:27] op_sel:[0,1,0] op_sel_hi:[1,1,1]
	s_waitcnt lgkmcnt(1)
	v_pk_mul_f32 v[22:23], v[6:7], v[52:53] op_sel:[0,0] op_sel_hi:[1,0]
	v_pk_mul_f32 v[30:31], v[68:69], v[92:93] op_sel:[0,0] op_sel_hi:[0,1]
	ds_read_b128 v[94:97], v47 offset:3840
	v_pk_fma_f32 v[22:23], v[8:9], v[52:53], v[22:23] op_sel:[0,1,0] op_sel_hi:[1,1,1]
	v_pk_mul_f32 v[32:33], v[68:69], v[92:93] op_sel:[1,0] op_sel_hi:[1,1]
	ds_read_b128 v[98:101], v47 offset:3856
	v_pk_fma_f32 v[22:23], v[10:11], v[54:55], v[22:23] op_sel:[0,0,0] op_sel_hi:[1,0,1]
	v_pk_mul_f32 v[34:35], v[70:71], v[92:93] op_sel:[0,0] op_sel_hi:[0,1]
	ds_read_b128 v[110:113], v47 offset:12032
	v_pk_fma_f32 v[22:23], v[12:13], v[54:55], v[22:23] op_sel:[0,1,0] op_sel_hi:[1,1,1]
	v_pk_mul_f32 v[36:37], v[70:71], v[92:93] op_sel:[1,0] op_sel_hi:[1,1]
	ds_read_b128 v[114:117], v47 offset:12048
	v_pk_fma_f32 v[22:23], v[14:15], v[56:57], v[22:23] op_sel:[0,0,0] op_sel_hi:[1,0,1]
	v_pk_mul_f32 v[38:39], v[72:73], v[92:93] op_sel:[0,0] op_sel_hi:[0,1]
	ds_read_b64 v[134:135], v48 offset:3840
	v_pk_fma_f32 v[22:23], v[16:17], v[56:57], v[22:23] op_sel:[0,1,0] op_sel_hi:[1,1,1]
	v_pk_mul_f32 v[40:41], v[72:73], v[92:93] op_sel:[1,0] op_sel_hi:[1,1]
	ds_read_b128 v[126:129], v47 offset:20224
	v_pk_fma_f32 v[22:23], v[18:19], v[58:59], v[22:23] op_sel:[0,0,0] op_sel_hi:[1,0,1]
	v_pk_mul_f32 v[42:43], v[74:75], v[92:93] op_sel:[0,0] op_sel_hi:[0,1]
	ds_read_b128 v[130:133], v47 offset:20240
	v_pk_fma_f32 v[22:23], v[20:21], v[58:59], v[22:23] op_sel:[0,1,0] op_sel_hi:[1,1,1]
	v_pk_mul_f32 v[44:45], v[74:75], v[92:93] op_sel:[1,0] op_sel_hi:[1,1]
	ds_read_b128 v[102:105], v47 offset:7936
	v_pk_fma_f32 v[30:31], v[84:85], v[6:7], v[30:31] op_sel:[0,0,0] op_sel_hi:[0,1,1]
	v_pk_fma_f32 v[32:33], v[84:85], v[8:9], v[32:33] op_sel:[1,0,0] op_sel_hi:[1,1,1]
	ds_read_b128 v[106:109], v47 offset:7952
	v_pk_fma_f32 v[34:35], v[86:87], v[10:11], v[34:35] op_sel:[0,0,0] op_sel_hi:[0,1,1]
	v_pk_fma_f32 v[36:37], v[86:87], v[12:13], v[36:37] op_sel:[1,0,0] op_sel_hi:[1,1,1]
	ds_read_b128 v[118:121], v47 offset:16128
	v_add_f32_dpp v22, v22, v22 quad_perm:[1,0,3,2] row_mask:0xf bank_mask:0xf
	v_add_f32_dpp v23, v23, v23 quad_perm:[1,0,3,2] row_mask:0xf bank_mask:0xf
	ds_read_b128 v[122:125], v47 offset:16144
	v_add_f32_dpp v26, v26, v26 quad_perm:[1,0,3,2] row_mask:0xf bank_mask:0xf
	v_add_f32_dpp v27, v27, v27 quad_perm:[1,0,3,2] row_mask:0xf bank_mask:0xf
	v_pk_fma_f32 v[38:39], v[88:89], v[14:15], v[38:39] op_sel:[0,0,0] op_sel_hi:[0,1,1]
	v_pk_fma_f32 v[40:41], v[88:89], v[16:17], v[40:41] op_sel:[1,0,0] op_sel_hi:[1,1,1]
	v_add_f32_dpp v22, v22, v22 quad_perm:[2,3,0,1] row_mask:0xf bank_mask:0xf
	v_add_f32_dpp v23, v23, v23 quad_perm:[2,3,0,1] row_mask:0xf bank_mask:0xf
	v_add_f32_dpp v26, v26, v26 quad_perm:[2,3,0,1] row_mask:0xf bank_mask:0xf
	v_add_f32_dpp v27, v27, v27 quad_perm:[2,3,0,1] row_mask:0xf bank_mask:0xf
	v_pk_fma_f32 v[42:43], v[90:91], v[18:19], v[42:43] op_sel:[0,0,0] op_sel_hi:[0,1,1]
	v_pk_fma_f32 v[44:45], v[90:91], v[20:21], v[44:45] op_sel:[1,0,0] op_sel_hi:[1,1,1]
	v_add_f32_dpp v22, v22, v22 row_half_mirror row_mask:0xf bank_mask:0xf
	v_add_f32_dpp v23, v23, v23 row_half_mirror row_mask:0xf bank_mask:0xf
	v_add_f32_dpp v26, v26, v26 row_half_mirror row_mask:0xf bank_mask:0xf
	v_add_f32_dpp v27, v27, v27 row_half_mirror row_mask:0xf bank_mask:0xf
	v_pk_fma_f32 v[6:7], v[60:61], v[22:23], v[30:31] op_sel:[0,0,0] op_sel_hi:[0,1,1] neg_lo:[0,1,0] neg_hi:[0,1,0]
	v_cvt_pk_f16_f32 v46, v26, v27
	v_pk_fma_f32 v[8:9], v[60:61], v[22:23], v[32:33] op_sel:[1,0,0] op_sel_hi:[1,1,1] neg_lo:[0,1,0] neg_hi:[0,1,0]
	v_pk_mul_f32 v[26:27], v[6:7], v[76:77] op_sel:[0,0] op_sel_hi:[1,0]
	v_pk_fma_f32 v[10:11], v[62:63], v[22:23], v[34:35] op_sel:[0,0,0] op_sel_hi:[0,1,1] neg_lo:[0,1,0] neg_hi:[0,1,0]
	v_pk_fma_f32 v[26:27], v[8:9], v[76:77], v[26:27] op_sel:[0,1,0] op_sel_hi:[1,1,1]
	v_pk_fma_f32 v[12:13], v[62:63], v[22:23], v[36:37] op_sel:[1,0,0] op_sel_hi:[1,1,1] neg_lo:[0,1,0] neg_hi:[0,1,0]
	v_pk_fma_f32 v[26:27], v[10:11], v[78:79], v[26:27] op_sel:[0,0,0] op_sel_hi:[1,0,1]
	v_pk_fma_f32 v[14:15], v[64:65], v[22:23], v[38:39] op_sel:[0,0,0] op_sel_hi:[0,1,1] neg_lo:[0,1,0] neg_hi:[0,1,0]
	v_pk_fma_f32 v[26:27], v[12:13], v[78:79], v[26:27] op_sel:[0,1,0] op_sel_hi:[1,1,1]
	v_pk_fma_f32 v[16:17], v[64:65], v[22:23], v[40:41] op_sel:[1,0,0] op_sel_hi:[1,1,1] neg_lo:[0,1,0] neg_hi:[0,1,0]
	v_pk_fma_f32 v[26:27], v[14:15], v[80:81], v[26:27] op_sel:[0,0,0] op_sel_hi:[1,0,1]
	v_pk_fma_f32 v[18:19], v[66:67], v[22:23], v[42:43] op_sel:[0,0,0] op_sel_hi:[0,1,1] neg_lo:[0,1,0] neg_hi:[0,1,0]
	v_pk_fma_f32 v[26:27], v[16:17], v[80:81], v[26:27] op_sel:[0,1,0] op_sel_hi:[1,1,1]
	v_pk_fma_f32 v[20:21], v[66:67], v[22:23], v[44:45] op_sel:[1,0,0] op_sel_hi:[1,1,1] neg_lo:[0,1,0] neg_hi:[0,1,0]
	v_pk_fma_f32 v[26:27], v[18:19], v[82:83], v[26:27] op_sel:[0,0,0] op_sel_hi:[1,0,1]
	ds_write_b32 v49, v46 offset:1664
	v_pk_fma_f32 v[26:27], v[20:21], v[82:83], v[26:27] op_sel:[0,1,0] op_sel_hi:[1,1,1]
	s_waitcnt lgkmcnt(1)
	v_pk_mul_f32 v[22:23], v[6:7], v[94:95] op_sel:[0,0] op_sel_hi:[1,0]
	v_pk_mul_f32 v[30:31], v[110:111], v[134:135] op_sel:[0,0] op_sel_hi:[0,1]
	v_pk_fma_f32 v[22:23], v[8:9], v[94:95], v[22:23] op_sel:[0,1,0] op_sel_hi:[1,1,1]
	v_pk_mul_f32 v[32:33], v[110:111], v[134:135] op_sel:[1,0] op_sel_hi:[1,1]
	v_pk_fma_f32 v[22:23], v[10:11], v[96:97], v[22:23] op_sel:[0,0,0] op_sel_hi:[1,0,1]
	v_pk_mul_f32 v[34:35], v[112:113], v[134:135] op_sel:[0,0] op_sel_hi:[0,1]
	v_pk_fma_f32 v[22:23], v[12:13], v[96:97], v[22:23] op_sel:[0,1,0] op_sel_hi:[1,1,1]
	v_pk_mul_f32 v[36:37], v[112:113], v[134:135] op_sel:[1,0] op_sel_hi:[1,1]
	v_pk_fma_f32 v[22:23], v[14:15], v[98:99], v[22:23] op_sel:[0,0,0] op_sel_hi:[1,0,1]
	v_pk_mul_f32 v[38:39], v[114:115], v[134:135] op_sel:[0,0] op_sel_hi:[0,1]
	v_pk_fma_f32 v[22:23], v[16:17], v[98:99], v[22:23] op_sel:[0,1,0] op_sel_hi:[1,1,1]
	v_pk_mul_f32 v[40:41], v[114:115], v[134:135] op_sel:[1,0] op_sel_hi:[1,1]
	v_pk_fma_f32 v[22:23], v[18:19], v[100:101], v[22:23] op_sel:[0,0,0] op_sel_hi:[1,0,1]
	v_pk_mul_f32 v[42:43], v[116:117], v[134:135] op_sel:[0,0] op_sel_hi:[0,1]
	v_pk_fma_f32 v[22:23], v[20:21], v[100:101], v[22:23] op_sel:[0,1,0] op_sel_hi:[1,1,1]
	v_pk_mul_f32 v[44:45], v[116:117], v[134:135] op_sel:[1,0] op_sel_hi:[1,1]
	v_pk_fma_f32 v[30:31], v[126:127], v[6:7], v[30:31] op_sel:[0,0,0] op_sel_hi:[0,1,1]
	v_pk_fma_f32 v[32:33], v[126:127], v[8:9], v[32:33] op_sel:[1,0,0] op_sel_hi:[1,1,1]
	v_pk_fma_f32 v[34:35], v[128:129], v[10:11], v[34:35] op_sel:[0,0,0] op_sel_hi:[0,1,1]
	v_pk_fma_f32 v[36:37], v[128:129], v[12:13], v[36:37] op_sel:[1,0,0] op_sel_hi:[1,1,1]
	v_add_f32_dpp v22, v22, v22 quad_perm:[1,0,3,2] row_mask:0xf bank_mask:0xf
	v_add_f32_dpp v23, v23, v23 quad_perm:[1,0,3,2] row_mask:0xf bank_mask:0xf
	v_add_f32_dpp v26, v26, v26 quad_perm:[1,0,3,2] row_mask:0xf bank_mask:0xf
	v_add_f32_dpp v27, v27, v27 quad_perm:[1,0,3,2] row_mask:0xf bank_mask:0xf
	v_pk_fma_f32 v[38:39], v[130:131], v[14:15], v[38:39] op_sel:[0,0,0] op_sel_hi:[0,1,1]
	v_pk_fma_f32 v[40:41], v[130:131], v[16:17], v[40:41] op_sel:[1,0,0] op_sel_hi:[1,1,1]
	v_add_f32_dpp v22, v22, v22 quad_perm:[2,3,0,1] row_mask:0xf bank_mask:0xf
	v_add_f32_dpp v23, v23, v23 quad_perm:[2,3,0,1] row_mask:0xf bank_mask:0xf
	v_add_f32_dpp v26, v26, v26 quad_perm:[2,3,0,1] row_mask:0xf bank_mask:0xf
	v_add_f32_dpp v27, v27, v27 quad_perm:[2,3,0,1] row_mask:0xf bank_mask:0xf
	v_pk_fma_f32 v[42:43], v[132:133], v[18:19], v[42:43] op_sel:[0,0,0] op_sel_hi:[0,1,1]
	v_pk_fma_f32 v[44:45], v[132:133], v[20:21], v[44:45] op_sel:[1,0,0] op_sel_hi:[1,1,1]
	v_add_f32_dpp v22, v22, v22 row_half_mirror row_mask:0xf bank_mask:0xf
	v_add_f32_dpp v23, v23, v23 row_half_mirror row_mask:0xf bank_mask:0xf
	v_add_f32_dpp v26, v26, v26 row_half_mirror row_mask:0xf bank_mask:0xf
	v_add_f32_dpp v27, v27, v27 row_half_mirror row_mask:0xf bank_mask:0xf
	v_pk_fma_f32 v[6:7], v[102:103], v[22:23], v[30:31] op_sel:[0,0,0] op_sel_hi:[0,1,1] neg_lo:[0,1,0] neg_hi:[0,1,0]
	v_cvt_pk_f16_f32 v46, v26, v27
	v_pk_fma_f32 v[8:9], v[102:103], v[22:23], v[32:33] op_sel:[1,0,0] op_sel_hi:[1,1,1] neg_lo:[0,1,0] neg_hi:[0,1,0]
	v_pk_mul_f32 v[26:27], v[6:7], v[118:119] op_sel:[0,0] op_sel_hi:[1,0]
	v_pk_fma_f32 v[10:11], v[104:105], v[22:23], v[34:35] op_sel:[0,0,0] op_sel_hi:[0,1,1] neg_lo:[0,1,0] neg_hi:[0,1,0]
	v_pk_fma_f32 v[26:27], v[8:9], v[118:119], v[26:27] op_sel:[0,1,0] op_sel_hi:[1,1,1]
	v_pk_fma_f32 v[12:13], v[104:105], v[22:23], v[36:37] op_sel:[1,0,0] op_sel_hi:[1,1,1] neg_lo:[0,1,0] neg_hi:[0,1,0]
	v_pk_fma_f32 v[26:27], v[10:11], v[120:121], v[26:27] op_sel:[0,0,0] op_sel_hi:[1,0,1]
	v_pk_fma_f32 v[14:15], v[106:107], v[22:23], v[38:39] op_sel:[0,0,0] op_sel_hi:[0,1,1] neg_lo:[0,1,0] neg_hi:[0,1,0]
	v_pk_fma_f32 v[26:27], v[12:13], v[120:121], v[26:27] op_sel:[0,1,0] op_sel_hi:[1,1,1]
	v_pk_fma_f32 v[16:17], v[106:107], v[22:23], v[40:41] op_sel:[1,0,0] op_sel_hi:[1,1,1] neg_lo:[0,1,0] neg_hi:[0,1,0]
	v_pk_fma_f32 v[26:27], v[14:15], v[122:123], v[26:27] op_sel:[0,0,0] op_sel_hi:[1,0,1]
	v_pk_fma_f32 v[18:19], v[108:109], v[22:23], v[42:43] op_sel:[0,0,0] op_sel_hi:[0,1,1] neg_lo:[0,1,0] neg_hi:[0,1,0]
	v_pk_fma_f32 v[26:27], v[16:17], v[122:123], v[26:27] op_sel:[0,1,0] op_sel_hi:[1,1,1]
	v_pk_fma_f32 v[20:21], v[108:109], v[22:23], v[44:45] op_sel:[1,0,0] op_sel_hi:[1,1,1] neg_lo:[0,1,0] neg_hi:[0,1,0]
	v_pk_fma_f32 v[26:27], v[18:19], v[124:125], v[26:27] op_sel:[0,0,0] op_sel_hi:[1,0,1]
	ds_write_b32 v49, v46 offset:1792
	v_pk_fma_f32 v[26:27], v[20:21], v[124:125], v[26:27] op_sel:[0,1,0] op_sel_hi:[1,1,1]
	s_nop 1
	v_add_f32_dpp v26, v26, v26 quad_perm:[1,0,3,2] row_mask:0xf bank_mask:0xf
	v_add_f32_dpp v27, v27, v27 quad_perm:[1,0,3,2] row_mask:0xf bank_mask:0xf
	s_nop 0
	v_add_f32_dpp v26, v26, v26 quad_perm:[2,3,0,1] row_mask:0xf bank_mask:0xf
	v_add_f32_dpp v27, v27, v27 quad_perm:[2,3,0,1] row_mask:0xf bank_mask:0xf
	s_nop 0
	v_add_f32_dpp v26, v26, v26 row_half_mirror row_mask:0xf bank_mask:0xf
	v_add_f32_dpp v27, v27, v27 row_half_mirror row_mask:0xf bank_mask:0xf
	s_nop 0
	v_cvt_pk_f16_f32 v46, v26, v27
	s_nop 0
	ds_write_b32 v49, v46 offset:1920
	s_cmp_eq_u32 s38, 0
	s_cbranch_scc1 .Lsc_nofin
	s_cmp_lg_u32 s53, 15
	s_cbranch_scc1 .Lsc_nofin
	s_lshr_b32 s55, s33, 4
	s_lshl_b32 s55, s55, 1
	s_lshr_b32 s56, s43, 4
	s_add_u32 s55, s55, s56
	s_lshl_b32 s55, s55, 2
	s_lshr_b32 s56, s42, 1
	s_add_u32 s55, s55, s56
	s_cmp_eq_u32 s38, 0
	s_cselect_b32 s54, s42, s55
	s_lshl_b32 s54, s54, 1
	s_add_u32 s54, s54, s44
	s_lshl_b32 s54, s54, 1
	s_add_u32 s54, s54, s50
	s_lshl_b32 s54, s54, 4
	s_add_u32 s54, s54, s46
	s_lshl_b32 s54, s54, 14
	s_add_u32 s54, s54, 0xc000000
	s_add_u32 s30, s34, s54
	s_addc_u32 s31, s35, 0
	v_mov_b32_e32 v52, v6
	v_mov_b32_e32 v60, v7
	v_mov_b32_e32 v53, v8
	v_mov_b32_e32 v61, v9
	v_mov_b32_e32 v54, v10
	v_mov_b32_e32 v62, v11
	v_mov_b32_e32 v55, v12
	v_mov_b32_e32 v63, v13
	v_mov_b32_e32 v56, v14
	v_mov_b32_e32 v64, v15
	v_mov_b32_e32 v57, v16
	v_mov_b32_e32 v65, v17
	v_mov_b32_e32 v58, v18
	v_mov_b32_e32 v66, v19
	v_mov_b32_e32 v59, v20
	v_mov_b32_e32 v67, v21
	s_nop 0
	global_store_dwordx4 v3, v[52:55], s[30:31]
	global_store_dwordx4 v3, v[56:59], s[30:31] offset:16
	global_store_dwordx4 v3, v[60:63], s[30:31] offset:256
	global_store_dwordx4 v3, v[64:67], s[30:31] offset:272
